# RWKV scan body shifted 4 bytes (most 8-byte instructions at 4 mod 8), later code kept at the same byte phase: placement sensitivity of the scan stream
# baseline (speedup 1.0000x reference)
; #define LAS __attribute__((address_space(3)))
; __device__ __forceinline__ float row16_sum(float v) { v += dpp_f<0xB1>(v); v += dpp_f<0x4E>(v); v += dpp_f<0x141>(v); v += dpp_f<0x140>(v); return v; }
; __device__ __forceinline__ void rwkv_scan_unit(LAS unsigned char* lds, const float* Wd, const float* V, const bf16_t* RKKB, float* Yraw, int p, int rg, int tid) {
;     ...
;     for (int c = 0; c < NCH; ++c) {
;         if (wave >= 4) { if (c + 2 < NCH) scan_load_chunk(lds + ((c + 2) % 3) * SCAN_SLOT_B, Wd, V, RKKB, p, rg, (c + 2) * SCAN_CH, tid - 256); }
;         else {
;             LAS const unsigned char* sl = lds + (c % 3) * SCAN_SLOT_B + kq * 16;
;             LAS const unsigned char* vl = lds + (c % 3) * SCAN_SLOT_B + 1280 + rl * 4;
;             float* yo = Yraw + ((size_t)p * SEQ + c * SCAN_CH + kq) * 64 + rg * 16 + rl;
;             f32x4 w = *(LAS const f32x4*)(sl), b = *(LAS const f32x4*)(sl + 256), k = *(LAS const f32x4*)(sl + 512), kk = *(LAS const f32x4*)(sl + 768), r = *(LAS const f32x4*)(sl + 1024);
;             float v = *(LAS const float*)(vl); float yp[16];
; #pragma unroll
;             for (int st = 0; st < SCAN_CH; ++st) {
;                 f32x4 wn = w, bn = b, kn = k, kkn = kk, rn = r; float vn = v;
;                 if (st + 1 < SCAN_CH) { const int o = (st + 1) * SCAN_STEP_B;
;                     wn = *(LAS const f32x4*)(sl + o); bn = *(LAS const f32x4*)(sl + o + 256); kn = *(LAS const f32x4*)(sl + o + 512); kkn = *(LAS const f32x4*)(sl + o + 768); rn = *(LAS const f32x4*)(sl + o + 1024);
;                     vn = *(LAS const float*)(vl + o); }
;                 float sa = (S[0] * kk[0] + S[1] * kk[1]) + (S[2] * kk[2] + S[3] * kk[3]);
;                 const f32x4 kvt = k * v;
;                 sa = -row16_sum(sa);
;                 S = S * w + (b * sa + kvt);
;                 yp[st & 15] = (S[0] * r[0] + S[1] * r[1]) + (S[2] * r[2] + S[3] * r[3]);
;                 if ((st & 15) == 15) yo[(size_t)(st - 15) * 64] = tr16_sum(yp, kq);
;                 w = wn; b = bn; k = kn; kk = kkn; r = rn; v = vn;
;             }
.LBB0_346:
	s_mov_b64 s[18:19], -1
	s_and_b64 vcc, exec, s[16:17]
	s_cbranch_vccz .LBB0_348
	s_nop 0
.Lscan_top:
	s_mul_i32 s18, s22, 0xab
	s_bfe_u32 s18, s18, 0x70009
	s_mul_i32 s18, s18, 3
	s_sub_i32 s18, s22, s18
	s_and_b32 s18, s18, 0xff
	s_mul_i32 s18, s18, 0xa800
	s_add_i32 s19, s18, 0xa800
	s_cmp_eq_u32 s19, 0x1f800
	s_cselect_b32 s19, 0, s19
	v_add_u32_e32 v84, s18, v71
	v_add_u32_e32 v83, s18, v72
	v_add_u32_e32 v86, s19, v71
	v_add_u32_e32 v85, s19, v72
	v_lshl_add_u64 v[62:63], v[60:61], 0, s[14:15]
	s_mov_b64 s[20:21], 0x16100000
	v_lshl_add_u64 v[88:89], v[62:63], 0, s[20:21]
	s_mov_b64 s[20:21], 0x16101000
	v_lshl_add_u64 v[90:91], v[62:63], 0, s[20:21]
	s_lshr_b32 s20, s18, 15
	s_lshl_b32 s20, s20, 11
	s_add_i32 s20, s20, 0x1f800
	v_lshl_add_u32 v96, v72, 5, s20
	s_lshr_b32 s21, s19, 15
	s_lshl_b32 s21, s21, 11
	s_add_i32 s21, s21, 0x1f800
	v_lshl_add_u32 v97, v72, 5, s21
	s_waitcnt lgkmcnt(5)
	v_pk_mul_f32 v[10:11], v[2:3], v[132:133]
	v_pk_fma_f32 v[10:11], v[4:5], v[134:135], v[10:11]
	v_pk_mul_f32 v[6:7], v[128:129], v[116:117] op_sel_hi:[1,0]
	v_add_f32_e32 v12, v10, v11
	v_pk_mul_f32 v[8:9], v[130:131], v[116:117] op_sel_hi:[1,0]
	v_pk_fma_f32 v[6:7], v[2:3], v[120:121], v[6:7]
	v_add_f32_dpp v12, v12, v12 quad_perm:[1,0,3,2] row_mask:0xf bank_mask:0xf bound_ctrl:1
	v_pk_fma_f32 v[8:9], v[4:5], v[122:123], v[8:9]
	ds_read_b128 v[180:183], v84 offset:3456
	v_add_f32_dpp v12, v12, v12 quad_perm:[2,3,0,1] row_mask:0xf bank_mask:0xf bound_ctrl:1
	ds_read_b128 v[168:171], v84 offset:2688
	ds_read_b128 v[176:179], v84 offset:3200
	v_add_f32_dpp v12, v12, v12 row_half_mirror row_mask:0xf bank_mask:0xf bound_ctrl:1
	ds_read_b128 v[172:175], v84 offset:2944
	ds_read_b128 v[184:187], v84 offset:3712
	v_add_f32_dpp v12, v12, v12 row_mirror row_mask:0xf bank_mask:0xf bound_ctrl:1
	v_pk_fma_f32 v[2:3], v[124:125], v[12:13], v[6:7] op_sel_hi:[1,0,1] neg_lo:[0,1,0] neg_hi:[0,1,0]
	v_pk_fma_f32 v[4:5], v[126:127], v[12:13], v[8:9] op_sel_hi:[1,0,1] neg_lo:[0,1,0] neg_hi:[0,1,0]
	s_waitcnt lgkmcnt(5)
	v_pk_mul_f32 v[10:11], v[2:3], v[156:157]
	v_pk_fma_f32 v[10:11], v[4:5], v[158:159], v[10:11]
	v_pk_mul_f32 v[14:15], v[2:3], v[136:137]
	v_add_f32_e32 v12, v10, v11
	v_pk_fma_f32 v[14:15], v[4:5], v[138:139], v[14:15]
	v_add_f32_e64 v100, v14, v15
	v_add_f32_dpp v12, v12, v12 quad_perm:[1,0,3,2] row_mask:0xf bank_mask:0xf bound_ctrl:1
	v_pk_mul_f32 v[6:7], v[152:153], v[116:117] op_sel:[0,1] op_sel_hi:[1,1]
	v_pk_mul_f32 v[8:9], v[154:155], v[116:117] op_sel:[0,1] op_sel_hi:[1,1]
	v_add_f32_dpp v12, v12, v12 quad_perm:[2,3,0,1] row_mask:0xf bank_mask:0xf bound_ctrl:1
	v_pk_fma_f32 v[6:7], v[2:3], v[144:145], v[6:7]
	v_pk_fma_f32 v[8:9], v[4:5], v[146:147], v[8:9]
	v_add_f32_dpp v12, v12, v12 row_half_mirror row_mask:0xf bank_mask:0xf bound_ctrl:1
	ds_read_b128 v[34:37], v84 offset:4800
	ds_read_b128 v[22:25], v84 offset:4032
	v_add_f32_dpp v12, v12, v12 row_mirror row_mask:0xf bank_mask:0xf bound_ctrl:1
	ds_read_b128 v[30:33], v84 offset:4544
	ds_read_b128 v[26:29], v84 offset:4288
	ds_read_b128 v[38:41], v84 offset:5056
	v_pk_fma_f32 v[2:3], v[148:149], v[12:13], v[6:7] op_sel_hi:[1,0,1] neg_lo:[0,1,0] neg_hi:[0,1,0]
	v_pk_fma_f32 v[4:5], v[150:151], v[12:13], v[8:9] op_sel_hi:[1,0,1] neg_lo:[0,1,0] neg_hi:[0,1,0]
	s_waitcnt lgkmcnt(5)
	v_pk_mul_f32 v[10:11], v[2:3], v[180:181]
	v_pk_fma_f32 v[10:11], v[4:5], v[182:183], v[10:11]
	v_pk_mul_f32 v[14:15], v[2:3], v[160:161]
	v_add_f32_e32 v12, v10, v11
	v_pk_fma_f32 v[14:15], v[4:5], v[162:163], v[14:15]
	v_add_f32_e64 v101, v14, v15
	v_add_f32_dpp v12, v12, v12 quad_perm:[1,0,3,2] row_mask:0xf bank_mask:0xf bound_ctrl:1
	v_pk_mul_f32 v[6:7], v[176:177], v[118:119] op_sel_hi:[1,0]
	v_pk_mul_f32 v[8:9], v[178:179], v[118:119] op_sel_hi:[1,0]
	v_add_f32_dpp v12, v12, v12 quad_perm:[2,3,0,1] row_mask:0xf bank_mask:0xf bound_ctrl:1
	v_pk_fma_f32 v[6:7], v[2:3], v[168:169], v[6:7]
	v_pk_fma_f32 v[8:9], v[4:5], v[170:171], v[8:9]
	v_add_f32_dpp v12, v12, v12 row_half_mirror row_mask:0xf bank_mask:0xf bound_ctrl:1
	ds_read_b128 v[132:135], v84 offset:6144
	ds_read_b128 v[120:123], v84 offset:5376
	v_add_f32_dpp v12, v12, v12 row_mirror row_mask:0xf bank_mask:0xf bound_ctrl:1
	ds_read_b128 v[128:131], v84 offset:5888
	ds_read_b128 v[92:95], v96 offset:16
	ds_read_b128 v[124:127], v84 offset:5632
	ds_read_b128 v[136:139], v84 offset:6400
	v_pk_fma_f32 v[2:3], v[172:173], v[12:13], v[6:7] op_sel_hi:[1,0,1] neg_lo:[0,1,0] neg_hi:[0,1,0]
	v_pk_fma_f32 v[4:5], v[174:175], v[12:13], v[8:9] op_sel_hi:[1,0,1] neg_lo:[0,1,0] neg_hi:[0,1,0]
	s_waitcnt lgkmcnt(6)
	v_pk_mul_f32 v[10:11], v[2:3], v[34:35]
	v_pk_fma_f32 v[10:11], v[4:5], v[36:37], v[10:11]
	v_pk_mul_f32 v[14:15], v[2:3], v[184:185]
	v_add_f32_e32 v12, v10, v11
	v_pk_fma_f32 v[14:15], v[4:5], v[186:187], v[14:15]
	v_add_f32_e64 v102, v14, v15
	v_add_f32_dpp v12, v12, v12 quad_perm:[1,0,3,2] row_mask:0xf bank_mask:0xf bound_ctrl:1
	v_pk_mul_f32 v[6:7], v[30:31], v[118:119] op_sel:[0,1] op_sel_hi:[1,1]
	v_pk_mul_f32 v[8:9], v[32:33], v[118:119] op_sel:[0,1] op_sel_hi:[1,1]
	v_add_f32_dpp v12, v12, v12 quad_perm:[2,3,0,1] row_mask:0xf bank_mask:0xf bound_ctrl:1
	v_pk_fma_f32 v[6:7], v[2:3], v[22:23], v[6:7]
	v_pk_fma_f32 v[8:9], v[4:5], v[24:25], v[8:9]
	v_add_f32_dpp v12, v12, v12 row_half_mirror row_mask:0xf bank_mask:0xf bound_ctrl:1
	ds_read_b128 v[156:159], v84 offset:7488
	ds_read_b128 v[144:147], v84 offset:6720
	v_add_f32_dpp v12, v12, v12 row_mirror row_mask:0xf bank_mask:0xf bound_ctrl:1
	ds_read_b128 v[152:155], v84 offset:7232
	ds_read_b128 v[148:151], v84 offset:6976
	ds_read_b128 v[160:163], v84 offset:7744
	v_pk_fma_f32 v[2:3], v[26:27], v[12:13], v[6:7] op_sel_hi:[1,0,1] neg_lo:[0,1,0] neg_hi:[0,1,0]
	v_pk_fma_f32 v[4:5], v[28:29], v[12:13], v[8:9] op_sel_hi:[1,0,1] neg_lo:[0,1,0] neg_hi:[0,1,0]
	s_waitcnt lgkmcnt(5)
; #define LAS __attribute__((address_space(3)))
; __device__ __forceinline__ float row16_sum(float v) { v += dpp_f<0xB1>(v); v += dpp_f<0x4E>(v); v += dpp_f<0x141>(v); v += dpp_f<0x140>(v); return v; }
; __device__ __forceinline__ void rwkv_scan_unit(LAS unsigned char* lds, const float* Wd, const float* V, const bf16_t* RKKB, float* Yraw, int p, int rg, int tid) {
;     ...
;             for (int st = 0; st < SCAN_CH; ++st) {
;                 f32x4 wn = w, bn = b, kn = k, kkn = kk, rn = r; float vn = v;
;                 if (st + 1 < SCAN_CH) { const int o = (st + 1) * SCAN_STEP_B;
;                     wn = *(LAS const f32x4*)(sl + o); bn = *(LAS const f32x4*)(sl + o + 256); kn = *(LAS const f32x4*)(sl + o + 512); kkn = *(LAS const f32x4*)(sl + o + 768); rn = *(LAS const f32x4*)(sl + o + 1024);
;                     vn = *(LAS const float*)(vl + o); }
;                 float sa = (S[0] * kk[0] + S[1] * kk[1]) + (S[2] * kk[2] + S[3] * kk[3]);
;                 const f32x4 kvt = k * v;
;                 sa = -row16_sum(sa);
;                 S = S * w + (b * sa + kvt);
;                 yp[st & 15] = (S[0] * r[0] + S[1] * r[1]) + (S[2] * r[2] + S[3] * r[3]);
;                 if ((st & 15) == 15) yo[(size_t)(st - 15) * 64] = tr16_sum(yp, kq);
;                 w = wn; b = bn; k = kn; kk = kkn; r = rn; v = vn;
;             }
	v_pk_mul_f32 v[10:11], v[2:3], v[132:133]
	v_pk_fma_f32 v[10:11], v[4:5], v[134:135], v[10:11]
	v_pk_mul_f32 v[14:15], v[2:3], v[38:39]
	v_add_f32_e32 v12, v10, v11
	v_pk_fma_f32 v[14:15], v[4:5], v[40:41], v[14:15]
	v_add_f32_e64 v103, v14, v15
	v_add_f32_dpp v12, v12, v12 quad_perm:[1,0,3,2] row_mask:0xf bank_mask:0xf bound_ctrl:1
	v_pk_mul_f32 v[6:7], v[128:129], v[92:93] op_sel_hi:[1,0]
	v_pk_mul_f32 v[8:9], v[130:131], v[92:93] op_sel_hi:[1,0]
	v_add_f32_dpp v12, v12, v12 quad_perm:[2,3,0,1] row_mask:0xf bank_mask:0xf bound_ctrl:1
	v_pk_fma_f32 v[6:7], v[2:3], v[120:121], v[6:7]
	v_pk_fma_f32 v[8:9], v[4:5], v[122:123], v[8:9]
	v_add_f32_dpp v12, v12, v12 row_half_mirror row_mask:0xf bank_mask:0xf bound_ctrl:1
	ds_read_b128 v[180:183], v84 offset:8832
	ds_read_b128 v[168:171], v84 offset:8064
	v_add_f32_dpp v12, v12, v12 row_mirror row_mask:0xf bank_mask:0xf bound_ctrl:1
	ds_read_b128 v[176:179], v84 offset:8576
	ds_read_b128 v[172:175], v84 offset:8320
	ds_read_b128 v[184:187], v84 offset:9088
	v_pk_fma_f32 v[2:3], v[124:125], v[12:13], v[6:7] op_sel_hi:[1,0,1] neg_lo:[0,1,0] neg_hi:[0,1,0]
	v_pk_fma_f32 v[4:5], v[126:127], v[12:13], v[8:9] op_sel_hi:[1,0,1] neg_lo:[0,1,0] neg_hi:[0,1,0]
	s_waitcnt lgkmcnt(5)
	v_pk_mul_f32 v[10:11], v[2:3], v[156:157]
	v_pk_fma_f32 v[10:11], v[4:5], v[158:159], v[10:11]
	v_pk_mul_f32 v[14:15], v[2:3], v[136:137]
	v_add_f32_e32 v12, v10, v11
	v_pk_fma_f32 v[14:15], v[4:5], v[138:139], v[14:15]
	v_add_f32_e64 v104, v14, v15
	v_add_f32_dpp v12, v12, v12 quad_perm:[1,0,3,2] row_mask:0xf bank_mask:0xf bound_ctrl:1
	v_pk_mul_f32 v[6:7], v[152:153], v[92:93] op_sel:[0,1] op_sel_hi:[1,1]
	v_pk_mul_f32 v[8:9], v[154:155], v[92:93] op_sel:[0,1] op_sel_hi:[1,1]
	v_add_f32_dpp v12, v12, v12 quad_perm:[2,3,0,1] row_mask:0xf bank_mask:0xf bound_ctrl:1
	v_pk_fma_f32 v[6:7], v[2:3], v[144:145], v[6:7]
	v_pk_fma_f32 v[8:9], v[4:5], v[146:147], v[8:9]
	v_add_f32_dpp v12, v12, v12 row_half_mirror row_mask:0xf bank_mask:0xf bound_ctrl:1
	ds_read_b128 v[34:37], v84 offset:10176
	ds_read_b128 v[22:25], v84 offset:9408
	v_add_f32_dpp v12, v12, v12 row_mirror row_mask:0xf bank_mask:0xf bound_ctrl:1
	ds_read_b128 v[30:33], v84 offset:9920
	ds_read_b128 v[26:29], v84 offset:9664
	ds_read_b128 v[38:41], v84 offset:10432
	v_pk_fma_f32 v[2:3], v[148:149], v[12:13], v[6:7] op_sel_hi:[1,0,1] neg_lo:[0,1,0] neg_hi:[0,1,0]
	v_pk_fma_f32 v[4:5], v[150:151], v[12:13], v[8:9] op_sel_hi:[1,0,1] neg_lo:[0,1,0] neg_hi:[0,1,0]
	s_waitcnt lgkmcnt(5)
	v_pk_mul_f32 v[10:11], v[2:3], v[180:181]
	v_pk_fma_f32 v[10:11], v[4:5], v[182:183], v[10:11]
	v_pk_mul_f32 v[14:15], v[2:3], v[160:161]
	v_add_f32_e32 v12, v10, v11
	v_pk_fma_f32 v[14:15], v[4:5], v[162:163], v[14:15]
	v_add_f32_e64 v105, v14, v15
	v_add_f32_dpp v12, v12, v12 quad_perm:[1,0,3,2] row_mask:0xf bank_mask:0xf bound_ctrl:1
	v_pk_mul_f32 v[6:7], v[176:177], v[94:95] op_sel_hi:[1,0]
	v_pk_mul_f32 v[8:9], v[178:179], v[94:95] op_sel_hi:[1,0]
	v_add_f32_dpp v12, v12, v12 quad_perm:[2,3,0,1] row_mask:0xf bank_mask:0xf bound_ctrl:1
	v_pk_fma_f32 v[6:7], v[2:3], v[168:169], v[6:7]
	v_pk_fma_f32 v[8:9], v[4:5], v[170:171], v[8:9]
	v_add_f32_dpp v12, v12, v12 row_half_mirror row_mask:0xf bank_mask:0xf bound_ctrl:1
	ds_read_b128 v[132:135], v84 offset:11520
	ds_read_b128 v[120:123], v84 offset:10752
	v_add_f32_dpp v12, v12, v12 row_mirror row_mask:0xf bank_mask:0xf bound_ctrl:1
	ds_read_b128 v[128:131], v84 offset:11264
	ds_read_b128 v[116:119], v96 offset:32
	ds_read_b128 v[124:127], v84 offset:11008
	ds_read_b128 v[136:139], v84 offset:11776
	v_pk_fma_f32 v[2:3], v[172:173], v[12:13], v[6:7] op_sel_hi:[1,0,1] neg_lo:[0,1,0] neg_hi:[0,1,0]
	v_pk_fma_f32 v[4:5], v[174:175], v[12:13], v[8:9] op_sel_hi:[1,0,1] neg_lo:[0,1,0] neg_hi:[0,1,0]
	s_waitcnt lgkmcnt(6)
	v_pk_mul_f32 v[10:11], v[2:3], v[34:35]
	v_pk_fma_f32 v[10:11], v[4:5], v[36:37], v[10:11]
	v_pk_mul_f32 v[14:15], v[2:3], v[184:185]
	v_add_f32_e32 v12, v10, v11
	v_pk_fma_f32 v[14:15], v[4:5], v[186:187], v[14:15]
	v_add_f32_e64 v106, v14, v15
	v_add_f32_dpp v12, v12, v12 quad_perm:[1,0,3,2] row_mask:0xf bank_mask:0xf bound_ctrl:1
	v_pk_mul_f32 v[6:7], v[30:31], v[94:95] op_sel:[0,1] op_sel_hi:[1,1]
	v_pk_mul_f32 v[8:9], v[32:33], v[94:95] op_sel:[0,1] op_sel_hi:[1,1]
	v_add_f32_dpp v12, v12, v12 quad_perm:[2,3,0,1] row_mask:0xf bank_mask:0xf bound_ctrl:1
	v_pk_fma_f32 v[6:7], v[2:3], v[22:23], v[6:7]
	v_pk_fma_f32 v[8:9], v[4:5], v[24:25], v[8:9]
	v_add_f32_dpp v12, v12, v12 row_half_mirror row_mask:0xf bank_mask:0xf bound_ctrl:1
	ds_read_b128 v[156:159], v84 offset:12864
	ds_read_b128 v[144:147], v84 offset:12096
	v_add_f32_dpp v12, v12, v12 row_mirror row_mask:0xf bank_mask:0xf bound_ctrl:1
	ds_read_b128 v[152:155], v84 offset:12608
	ds_read_b128 v[148:151], v84 offset:12352
	ds_read_b128 v[160:163], v84 offset:13120
	v_pk_fma_f32 v[2:3], v[26:27], v[12:13], v[6:7] op_sel_hi:[1,0,1] neg_lo:[0,1,0] neg_hi:[0,1,0]
	v_pk_fma_f32 v[4:5], v[28:29], v[12:13], v[8:9] op_sel_hi:[1,0,1] neg_lo:[0,1,0] neg_hi:[0,1,0]
	s_waitcnt lgkmcnt(5)
; #define LAS __attribute__((address_space(3)))
; template <int CTRL> __device__ __forceinline__ float dpp_f(float v) { return __int_as_float(__builtin_amdgcn_update_dpp(0, __float_as_int(v), CTRL, 0xf, 0xf, true)); }
; __device__ __forceinline__ float row16_sum(float v) { v += dpp_f<0xB1>(v); v += dpp_f<0x4E>(v); v += dpp_f<0x141>(v); v += dpp_f<0x140>(v); return v; }
; __device__ __forceinline__ float tr16_sum(const float (&p)[16], int kq) {
;     const bool b3 = (kq & 8) != 0, b2 = (kq & 4) != 0, b1 = (kq & 2) != 0, b0 = (kq & 1) != 0;
;     float q[8], r[4], u[2];
; #pragma unroll
;     for (int t = 0; t < 8; ++t) { const float keep = b3 ? p[t + 8] : p[t], send = b3 ? p[t] : p[t + 8]; q[t] = keep + dpp_f<0x140>(send); }
; #pragma unroll
;     for (int t = 0; t < 4; ++t) { const float keep = b2 ? q[t + 4] : q[t], send = b2 ? q[t] : q[t + 4]; r[t] = keep + dpp_f<0x141>(send); }
; #pragma unroll
;     for (int t = 0; t < 2; ++t) { const float keep = b1 ? r[t + 2] : r[t], send = b1 ? r[t] : r[t + 2]; u[t] = keep + dpp_f<0x4E>(send); }
;     const float keep = b0 ? u[1] : u[0], send = b0 ? u[0] : u[1];
;     return keep + dpp_f<0xB1>(send);
; __device__ __forceinline__ void rwkv_scan_unit(LAS unsigned char* lds, const float* Wd, const float* V, const bf16_t* RKKB, float* Yraw, int p, int rg, int tid) {
;     ...
;             for (int st = 0; st < SCAN_CH; ++st) {
;                 f32x4 wn = w, bn = b, kn = k, kkn = kk, rn = r; float vn = v;
;                 if (st + 1 < SCAN_CH) { const int o = (st + 1) * SCAN_STEP_B;
;                     wn = *(LAS const f32x4*)(sl + o); bn = *(LAS const f32x4*)(sl + o + 256); kn = *(LAS const f32x4*)(sl + o + 512); kkn = *(LAS const f32x4*)(sl + o + 768); rn = *(LAS const f32x4*)(sl + o + 1024);
;                     vn = *(LAS const float*)(vl + o); }
;                 float sa = (S[0] * kk[0] + S[1] * kk[1]) + (S[2] * kk[2] + S[3] * kk[3]);
;                 const f32x4 kvt = k * v;
;                 sa = -row16_sum(sa);
;                 S = S * w + (b * sa + kvt);
;                 yp[st & 15] = (S[0] * r[0] + S[1] * r[1]) + (S[2] * r[2] + S[3] * r[3]);
;                 if ((st & 15) == 15) yo[(size_t)(st - 15) * 64] = tr16_sum(yp, kq);
;                 w = wn; b = bn; k = kn; kk = kkn; r = rn; v = vn;
;             }
	v_pk_mul_f32 v[10:11], v[2:3], v[132:133]
	v_pk_fma_f32 v[10:11], v[4:5], v[134:135], v[10:11]
	v_pk_mul_f32 v[14:15], v[2:3], v[38:39]
	v_add_f32_e32 v12, v10, v11
	v_pk_fma_f32 v[14:15], v[4:5], v[40:41], v[14:15]
	v_add_f32_e64 v107, v14, v15
	v_add_f32_dpp v12, v12, v12 quad_perm:[1,0,3,2] row_mask:0xf bank_mask:0xf bound_ctrl:1
	v_pk_mul_f32 v[6:7], v[128:129], v[116:117] op_sel_hi:[1,0]
	v_pk_mul_f32 v[8:9], v[130:131], v[116:117] op_sel_hi:[1,0]
	v_add_f32_dpp v12, v12, v12 quad_perm:[2,3,0,1] row_mask:0xf bank_mask:0xf bound_ctrl:1
	v_pk_fma_f32 v[6:7], v[2:3], v[120:121], v[6:7]
	v_pk_fma_f32 v[8:9], v[4:5], v[122:123], v[8:9]
	v_add_f32_dpp v12, v12, v12 row_half_mirror row_mask:0xf bank_mask:0xf bound_ctrl:1
	ds_read_b128 v[180:183], v84 offset:14208
	ds_read_b128 v[168:171], v84 offset:13440
	v_add_f32_dpp v12, v12, v12 row_mirror row_mask:0xf bank_mask:0xf bound_ctrl:1
	ds_read_b128 v[176:179], v84 offset:13952
	ds_read_b128 v[172:175], v84 offset:13696
	ds_read_b128 v[184:187], v84 offset:14464
	v_pk_fma_f32 v[2:3], v[124:125], v[12:13], v[6:7] op_sel_hi:[1,0,1] neg_lo:[0,1,0] neg_hi:[0,1,0]
	v_pk_fma_f32 v[4:5], v[126:127], v[12:13], v[8:9] op_sel_hi:[1,0,1] neg_lo:[0,1,0] neg_hi:[0,1,0]
	s_waitcnt lgkmcnt(5)
	v_pk_mul_f32 v[10:11], v[2:3], v[156:157]
	v_pk_fma_f32 v[10:11], v[4:5], v[158:159], v[10:11]
	v_pk_mul_f32 v[14:15], v[2:3], v[136:137]
	v_add_f32_e32 v12, v10, v11
	v_pk_fma_f32 v[14:15], v[4:5], v[138:139], v[14:15]
	v_add_f32_e64 v44, v14, v15
	v_add_f32_dpp v12, v12, v12 quad_perm:[1,0,3,2] row_mask:0xf bank_mask:0xf bound_ctrl:1
	v_add_f32_dpp v100, v100, v100 row_mirror row_mask:0xf bank_mask:0x3 bound_ctrl:1
	v_add_f32_dpp v100, v44, v44 row_mirror row_mask:0xf bank_mask:0xc bound_ctrl:1
	v_add_f32_dpp v12, v12, v12 quad_perm:[2,3,0,1] row_mask:0xf bank_mask:0xf bound_ctrl:1
	v_pk_mul_f32 v[6:7], v[152:153], v[116:117] op_sel:[0,1] op_sel_hi:[1,1]
	v_pk_mul_f32 v[8:9], v[154:155], v[116:117] op_sel:[0,1] op_sel_hi:[1,1]
	v_add_f32_dpp v12, v12, v12 row_half_mirror row_mask:0xf bank_mask:0xf bound_ctrl:1
	v_pk_fma_f32 v[6:7], v[2:3], v[144:145], v[6:7]
	v_pk_fma_f32 v[8:9], v[4:5], v[146:147], v[8:9]
	v_add_f32_dpp v12, v12, v12 row_mirror row_mask:0xf bank_mask:0xf bound_ctrl:1
	ds_read_b128 v[34:37], v84 offset:15552
	ds_read_b128 v[22:25], v84 offset:14784
	ds_read_b128 v[30:33], v84 offset:15296
	ds_read_b128 v[26:29], v84 offset:15040
	ds_read_b128 v[38:41], v84 offset:15808
	v_pk_fma_f32 v[2:3], v[148:149], v[12:13], v[6:7] op_sel_hi:[1,0,1] neg_lo:[0,1,0] neg_hi:[0,1,0]
	v_pk_fma_f32 v[4:5], v[150:151], v[12:13], v[8:9] op_sel_hi:[1,0,1] neg_lo:[0,1,0] neg_hi:[0,1,0]
	s_waitcnt lgkmcnt(5)
	v_pk_mul_f32 v[10:11], v[2:3], v[180:181]
	v_pk_fma_f32 v[10:11], v[4:5], v[182:183], v[10:11]
	v_pk_mul_f32 v[14:15], v[2:3], v[160:161]
	v_add_f32_e32 v12, v10, v11
	v_pk_fma_f32 v[14:15], v[4:5], v[162:163], v[14:15]
	v_add_f32_e64 v44, v14, v15
	v_add_f32_dpp v12, v12, v12 quad_perm:[1,0,3,2] row_mask:0xf bank_mask:0xf bound_ctrl:1
	v_add_f32_dpp v101, v101, v101 row_mirror row_mask:0xf bank_mask:0x3 bound_ctrl:1
	v_add_f32_dpp v101, v44, v44 row_mirror row_mask:0xf bank_mask:0xc bound_ctrl:1
	v_add_f32_dpp v12, v12, v12 quad_perm:[2,3,0,1] row_mask:0xf bank_mask:0xf bound_ctrl:1
	v_pk_mul_f32 v[6:7], v[176:177], v[118:119] op_sel_hi:[1,0]
	v_pk_mul_f32 v[8:9], v[178:179], v[118:119] op_sel_hi:[1,0]
	v_add_f32_dpp v12, v12, v12 row_half_mirror row_mask:0xf bank_mask:0xf bound_ctrl:1
	v_pk_fma_f32 v[6:7], v[2:3], v[168:169], v[6:7]
	v_pk_fma_f32 v[8:9], v[4:5], v[170:171], v[8:9]
	v_add_f32_dpp v12, v12, v12 row_mirror row_mask:0xf bank_mask:0xf bound_ctrl:1
	ds_read_b128 v[132:135], v84 offset:16896
	ds_read_b128 v[120:123], v84 offset:16128
	ds_read_b128 v[128:131], v84 offset:16640
	ds_read_b128 v[92:95], v96 offset:48
	ds_read_b128 v[124:127], v84 offset:16384
	ds_read_b128 v[136:139], v84 offset:17152
	v_pk_fma_f32 v[2:3], v[172:173], v[12:13], v[6:7] op_sel_hi:[1,0,1] neg_lo:[0,1,0] neg_hi:[0,1,0]
	v_pk_fma_f32 v[4:5], v[174:175], v[12:13], v[8:9] op_sel_hi:[1,0,1] neg_lo:[0,1,0] neg_hi:[0,1,0]
	s_waitcnt lgkmcnt(6)
	v_pk_mul_f32 v[10:11], v[2:3], v[34:35]
	v_pk_fma_f32 v[10:11], v[4:5], v[36:37], v[10:11]
	v_pk_mul_f32 v[14:15], v[2:3], v[184:185]
	v_add_f32_e32 v12, v10, v11
	v_pk_fma_f32 v[14:15], v[4:5], v[186:187], v[14:15]
	v_add_f32_e64 v44, v14, v15
	v_add_f32_dpp v12, v12, v12 quad_perm:[1,0,3,2] row_mask:0xf bank_mask:0xf bound_ctrl:1
	v_add_f32_dpp v102, v102, v102 row_mirror row_mask:0xf bank_mask:0x3 bound_ctrl:1
	v_add_f32_dpp v102, v44, v44 row_mirror row_mask:0xf bank_mask:0xc bound_ctrl:1
	v_add_f32_dpp v12, v12, v12 quad_perm:[2,3,0,1] row_mask:0xf bank_mask:0xf bound_ctrl:1
	v_pk_mul_f32 v[6:7], v[30:31], v[118:119] op_sel:[0,1] op_sel_hi:[1,1]
	v_pk_mul_f32 v[8:9], v[32:33], v[118:119] op_sel:[0,1] op_sel_hi:[1,1]
	v_add_f32_dpp v12, v12, v12 row_half_mirror row_mask:0xf bank_mask:0xf bound_ctrl:1
	v_pk_fma_f32 v[6:7], v[2:3], v[22:23], v[6:7]
	v_pk_fma_f32 v[8:9], v[4:5], v[24:25], v[8:9]
	v_add_f32_dpp v12, v12, v12 row_mirror row_mask:0xf bank_mask:0xf bound_ctrl:1
	ds_read_b128 v[156:159], v84 offset:18240
	ds_read_b128 v[144:147], v84 offset:17472
	ds_read_b128 v[152:155], v84 offset:17984
	ds_read_b128 v[148:151], v84 offset:17728
	ds_read_b128 v[160:163], v84 offset:18496
	v_pk_fma_f32 v[2:3], v[26:27], v[12:13], v[6:7] op_sel_hi:[1,0,1] neg_lo:[0,1,0] neg_hi:[0,1,0]
	v_pk_fma_f32 v[4:5], v[28:29], v[12:13], v[8:9] op_sel_hi:[1,0,1] neg_lo:[0,1,0] neg_hi:[0,1,0]
	s_waitcnt lgkmcnt(5)
; #define LAS __attribute__((address_space(3)))
; template <int CTRL> __device__ __forceinline__ float dpp_f(float v) { return __int_as_float(__builtin_amdgcn_update_dpp(0, __float_as_int(v), CTRL, 0xf, 0xf, true)); }
; __device__ __forceinline__ float row16_sum(float v) { v += dpp_f<0xB1>(v); v += dpp_f<0x4E>(v); v += dpp_f<0x141>(v); v += dpp_f<0x140>(v); return v; }
; __device__ __forceinline__ float tr16_sum(const float (&p)[16], int kq) {
;     const bool b3 = (kq & 8) != 0, b2 = (kq & 4) != 0, b1 = (kq & 2) != 0, b0 = (kq & 1) != 0;
;     float q[8], r[4], u[2];
; #pragma unroll
;     for (int t = 0; t < 8; ++t) { const float keep = b3 ? p[t + 8] : p[t], send = b3 ? p[t] : p[t + 8]; q[t] = keep + dpp_f<0x140>(send); }
; #pragma unroll
;     for (int t = 0; t < 4; ++t) { const float keep = b2 ? q[t + 4] : q[t], send = b2 ? q[t] : q[t + 4]; r[t] = keep + dpp_f<0x141>(send); }
; #pragma unroll
;     for (int t = 0; t < 2; ++t) { const float keep = b1 ? r[t + 2] : r[t], send = b1 ? r[t] : r[t + 2]; u[t] = keep + dpp_f<0x4E>(send); }
;     const float keep = b0 ? u[1] : u[0], send = b0 ? u[0] : u[1];
;     return keep + dpp_f<0xB1>(send);
; __device__ __forceinline__ void rwkv_scan_unit(LAS unsigned char* lds, const float* Wd, const float* V, const bf16_t* RKKB, float* Yraw, int p, int rg, int tid) {
;     ...
;             for (int st = 0; st < SCAN_CH; ++st) {
;                 f32x4 wn = w, bn = b, kn = k, kkn = kk, rn = r; float vn = v;
;                 if (st + 1 < SCAN_CH) { const int o = (st + 1) * SCAN_STEP_B;
;                     wn = *(LAS const f32x4*)(sl + o); bn = *(LAS const f32x4*)(sl + o + 256); kn = *(LAS const f32x4*)(sl + o + 512); kkn = *(LAS const f32x4*)(sl + o + 768); rn = *(LAS const f32x4*)(sl + o + 1024);
;                     vn = *(LAS const float*)(vl + o); }
;                 float sa = (S[0] * kk[0] + S[1] * kk[1]) + (S[2] * kk[2] + S[3] * kk[3]);
;                 const f32x4 kvt = k * v;
;                 sa = -row16_sum(sa);
;                 S = S * w + (b * sa + kvt);
;                 yp[st & 15] = (S[0] * r[0] + S[1] * r[1]) + (S[2] * r[2] + S[3] * r[3]);
;                 if ((st & 15) == 15) yo[(size_t)(st - 15) * 64] = tr16_sum(yp, kq);
;                 w = wn; b = bn; k = kn; kk = kkn; r = rn; v = vn;
;             }
	v_pk_mul_f32 v[10:11], v[2:3], v[132:133]
	v_pk_fma_f32 v[10:11], v[4:5], v[134:135], v[10:11]
	v_pk_mul_f32 v[14:15], v[2:3], v[38:39]
	v_add_f32_e32 v12, v10, v11
	v_pk_fma_f32 v[14:15], v[4:5], v[40:41], v[14:15]
	v_add_f32_e64 v44, v14, v15
	v_add_f32_dpp v12, v12, v12 quad_perm:[1,0,3,2] row_mask:0xf bank_mask:0xf bound_ctrl:1
	v_add_f32_dpp v103, v103, v103 row_mirror row_mask:0xf bank_mask:0x3 bound_ctrl:1
	v_add_f32_dpp v103, v44, v44 row_mirror row_mask:0xf bank_mask:0xc bound_ctrl:1
	v_add_f32_dpp v12, v12, v12 quad_perm:[2,3,0,1] row_mask:0xf bank_mask:0xf bound_ctrl:1
	v_pk_mul_f32 v[6:7], v[128:129], v[92:93] op_sel_hi:[1,0]
	v_pk_mul_f32 v[8:9], v[130:131], v[92:93] op_sel_hi:[1,0]
	v_add_f32_dpp v12, v12, v12 row_half_mirror row_mask:0xf bank_mask:0xf bound_ctrl:1
	v_pk_fma_f32 v[6:7], v[2:3], v[120:121], v[6:7]
	v_pk_fma_f32 v[8:9], v[4:5], v[122:123], v[8:9]
	v_add_f32_dpp v12, v12, v12 row_mirror row_mask:0xf bank_mask:0xf bound_ctrl:1
	ds_read_b128 v[180:183], v84 offset:19584
	ds_read_b128 v[168:171], v84 offset:18816
	ds_read_b128 v[176:179], v84 offset:19328
	ds_read_b128 v[172:175], v84 offset:19072
	ds_read_b128 v[184:187], v84 offset:19840
	v_pk_fma_f32 v[2:3], v[124:125], v[12:13], v[6:7] op_sel_hi:[1,0,1] neg_lo:[0,1,0] neg_hi:[0,1,0]
	v_pk_fma_f32 v[4:5], v[126:127], v[12:13], v[8:9] op_sel_hi:[1,0,1] neg_lo:[0,1,0] neg_hi:[0,1,0]
	s_waitcnt lgkmcnt(5)
	v_pk_mul_f32 v[10:11], v[2:3], v[156:157]
	v_pk_fma_f32 v[10:11], v[4:5], v[158:159], v[10:11]
	v_pk_mul_f32 v[14:15], v[2:3], v[136:137]
	v_add_f32_e32 v12, v10, v11
	v_pk_fma_f32 v[14:15], v[4:5], v[138:139], v[14:15]
	v_add_f32_e64 v44, v14, v15
	v_add_f32_dpp v12, v12, v12 quad_perm:[1,0,3,2] row_mask:0xf bank_mask:0xf bound_ctrl:1
	v_add_f32_dpp v104, v104, v104 row_mirror row_mask:0xf bank_mask:0x3 bound_ctrl:1
	v_add_f32_dpp v104, v44, v44 row_mirror row_mask:0xf bank_mask:0xc bound_ctrl:1
	v_add_f32_dpp v12, v12, v12 quad_perm:[2,3,0,1] row_mask:0xf bank_mask:0xf bound_ctrl:1
	v_pk_mul_f32 v[6:7], v[152:153], v[92:93] op_sel:[0,1] op_sel_hi:[1,1]
	v_pk_mul_f32 v[8:9], v[154:155], v[92:93] op_sel:[0,1] op_sel_hi:[1,1]
	v_add_f32_dpp v12, v12, v12 row_half_mirror row_mask:0xf bank_mask:0xf bound_ctrl:1
	v_pk_fma_f32 v[6:7], v[2:3], v[144:145], v[6:7]
	v_pk_fma_f32 v[8:9], v[4:5], v[146:147], v[8:9]
	v_add_f32_dpp v12, v12, v12 row_mirror row_mask:0xf bank_mask:0xf bound_ctrl:1
	ds_read_b128 v[34:37], v84 offset:20928
	ds_read_b128 v[22:25], v84 offset:20160
	ds_read_b128 v[30:33], v84 offset:20672
	ds_read_b128 v[26:29], v84 offset:20416
	ds_read_b128 v[38:41], v84 offset:21184
	v_pk_fma_f32 v[2:3], v[148:149], v[12:13], v[6:7] op_sel_hi:[1,0,1] neg_lo:[0,1,0] neg_hi:[0,1,0]
	v_pk_fma_f32 v[4:5], v[150:151], v[12:13], v[8:9] op_sel_hi:[1,0,1] neg_lo:[0,1,0] neg_hi:[0,1,0]
	s_waitcnt lgkmcnt(5)
	v_pk_mul_f32 v[10:11], v[2:3], v[180:181]
	v_pk_fma_f32 v[10:11], v[4:5], v[182:183], v[10:11]
	v_pk_mul_f32 v[14:15], v[2:3], v[160:161]
	v_add_f32_e32 v12, v10, v11
	v_pk_fma_f32 v[14:15], v[4:5], v[162:163], v[14:15]
	v_add_f32_e64 v44, v14, v15
	v_add_f32_dpp v12, v12, v12 quad_perm:[1,0,3,2] row_mask:0xf bank_mask:0xf bound_ctrl:1
	v_add_f32_dpp v105, v105, v105 row_mirror row_mask:0xf bank_mask:0x3 bound_ctrl:1
	v_add_f32_dpp v105, v44, v44 row_mirror row_mask:0xf bank_mask:0xc bound_ctrl:1
	v_add_f32_dpp v12, v12, v12 quad_perm:[2,3,0,1] row_mask:0xf bank_mask:0xf bound_ctrl:1
	v_pk_mul_f32 v[6:7], v[176:177], v[94:95] op_sel_hi:[1,0]
	v_pk_mul_f32 v[8:9], v[178:179], v[94:95] op_sel_hi:[1,0]
	v_add_f32_dpp v12, v12, v12 row_half_mirror row_mask:0xf bank_mask:0xf bound_ctrl:1
	v_pk_fma_f32 v[6:7], v[2:3], v[168:169], v[6:7]
	v_pk_fma_f32 v[8:9], v[4:5], v[170:171], v[8:9]
	v_add_f32_dpp v12, v12, v12 row_mirror row_mask:0xf bank_mask:0xf bound_ctrl:1
	ds_read_b128 v[132:135], v84 offset:22272
	ds_read_b128 v[120:123], v84 offset:21504
	ds_read_b128 v[128:131], v84 offset:22016
	ds_read_b128 v[116:119], v96 offset:64
	ds_read_b128 v[124:127], v84 offset:21760
	ds_read_b128 v[136:139], v84 offset:22528
	v_pk_fma_f32 v[2:3], v[172:173], v[12:13], v[6:7] op_sel_hi:[1,0,1] neg_lo:[0,1,0] neg_hi:[0,1,0]
	v_pk_fma_f32 v[4:5], v[174:175], v[12:13], v[8:9] op_sel_hi:[1,0,1] neg_lo:[0,1,0] neg_hi:[0,1,0]
	s_waitcnt lgkmcnt(6)
	v_pk_mul_f32 v[10:11], v[2:3], v[34:35]
	v_pk_fma_f32 v[10:11], v[4:5], v[36:37], v[10:11]
	v_pk_mul_f32 v[14:15], v[2:3], v[184:185]
	v_add_f32_e32 v12, v10, v11
	v_pk_fma_f32 v[14:15], v[4:5], v[186:187], v[14:15]
	v_add_f32_e64 v44, v14, v15
	v_add_f32_dpp v12, v12, v12 quad_perm:[1,0,3,2] row_mask:0xf bank_mask:0xf bound_ctrl:1
	v_add_f32_dpp v106, v106, v106 row_mirror row_mask:0xf bank_mask:0x3 bound_ctrl:1
	v_add_f32_dpp v106, v44, v44 row_mirror row_mask:0xf bank_mask:0xc bound_ctrl:1
	v_add_f32_dpp v12, v12, v12 quad_perm:[2,3,0,1] row_mask:0xf bank_mask:0xf bound_ctrl:1
	v_pk_mul_f32 v[6:7], v[30:31], v[94:95] op_sel:[0,1] op_sel_hi:[1,1]
	v_pk_mul_f32 v[8:9], v[32:33], v[94:95] op_sel:[0,1] op_sel_hi:[1,1]
	v_add_f32_dpp v12, v12, v12 row_half_mirror row_mask:0xf bank_mask:0xf bound_ctrl:1
	v_pk_fma_f32 v[6:7], v[2:3], v[22:23], v[6:7]
	v_pk_fma_f32 v[8:9], v[4:5], v[24:25], v[8:9]
	v_add_f32_dpp v12, v12, v12 row_mirror row_mask:0xf bank_mask:0xf bound_ctrl:1
	ds_read_b128 v[156:159], v84 offset:23616
	ds_read_b128 v[144:147], v84 offset:22848
	ds_read_b128 v[152:155], v84 offset:23360
	ds_read_b128 v[148:151], v84 offset:23104
	ds_read_b128 v[160:163], v84 offset:23872
	v_pk_fma_f32 v[2:3], v[26:27], v[12:13], v[6:7] op_sel_hi:[1,0,1] neg_lo:[0,1,0] neg_hi:[0,1,0]
	v_pk_fma_f32 v[4:5], v[28:29], v[12:13], v[8:9] op_sel_hi:[1,0,1] neg_lo:[0,1,0] neg_hi:[0,1,0]
	s_waitcnt lgkmcnt(5)
; #define LAS __attribute__((address_space(3)))
; template <int CTRL> __device__ __forceinline__ float dpp_f(float v) { return __int_as_float(__builtin_amdgcn_update_dpp(0, __float_as_int(v), CTRL, 0xf, 0xf, true)); }
; __device__ __forceinline__ float row16_sum(float v) { v += dpp_f<0xB1>(v); v += dpp_f<0x4E>(v); v += dpp_f<0x141>(v); v += dpp_f<0x140>(v); return v; }
; __device__ __forceinline__ float tr16_sum(const float (&p)[16], int kq) {
;     const bool b3 = (kq & 8) != 0, b2 = (kq & 4) != 0, b1 = (kq & 2) != 0, b0 = (kq & 1) != 0;
;     float q[8], r[4], u[2];
; #pragma unroll
;     for (int t = 0; t < 8; ++t) { const float keep = b3 ? p[t + 8] : p[t], send = b3 ? p[t] : p[t + 8]; q[t] = keep + dpp_f<0x140>(send); }
; #pragma unroll
;     for (int t = 0; t < 4; ++t) { const float keep = b2 ? q[t + 4] : q[t], send = b2 ? q[t] : q[t + 4]; r[t] = keep + dpp_f<0x141>(send); }
; #pragma unroll
;     for (int t = 0; t < 2; ++t) { const float keep = b1 ? r[t + 2] : r[t], send = b1 ? r[t] : r[t + 2]; u[t] = keep + dpp_f<0x4E>(send); }
;     const float keep = b0 ? u[1] : u[0], send = b0 ? u[0] : u[1];
;     return keep + dpp_f<0xB1>(send);
; __device__ __forceinline__ void rwkv_scan_unit(LAS unsigned char* lds, const float* Wd, const float* V, const bf16_t* RKKB, float* Yraw, int p, int rg, int tid) {
;     ...
;             for (int st = 0; st < SCAN_CH; ++st) {
;                 f32x4 wn = w, bn = b, kn = k, kkn = kk, rn = r; float vn = v;
;                 if (st + 1 < SCAN_CH) { const int o = (st + 1) * SCAN_STEP_B;
;                     wn = *(LAS const f32x4*)(sl + o); bn = *(LAS const f32x4*)(sl + o + 256); kn = *(LAS const f32x4*)(sl + o + 512); kkn = *(LAS const f32x4*)(sl + o + 768); rn = *(LAS const f32x4*)(sl + o + 1024);
;                     vn = *(LAS const float*)(vl + o); }
;                 float sa = (S[0] * kk[0] + S[1] * kk[1]) + (S[2] * kk[2] + S[3] * kk[3]);
;                 const f32x4 kvt = k * v;
;                 sa = -row16_sum(sa);
;                 S = S * w + (b * sa + kvt);
;                 yp[st & 15] = (S[0] * r[0] + S[1] * r[1]) + (S[2] * r[2] + S[3] * r[3]);
;                 if ((st & 15) == 15) yo[(size_t)(st - 15) * 64] = tr16_sum(yp, kq);
;                 w = wn; b = bn; k = kn; kk = kkn; r = rn; v = vn;
;             }
	v_pk_mul_f32 v[10:11], v[2:3], v[132:133]
	v_pk_fma_f32 v[10:11], v[4:5], v[134:135], v[10:11]
	v_pk_mul_f32 v[14:15], v[2:3], v[38:39]
	v_add_f32_e32 v12, v10, v11
	v_pk_fma_f32 v[14:15], v[4:5], v[40:41], v[14:15]
	v_add_f32_e64 v44, v14, v15
	v_add_f32_dpp v107, v107, v107 row_mirror row_mask:0xf bank_mask:0x3 bound_ctrl:1
	s_nop 0
	v_add_f32_dpp v107, v44, v44 row_mirror row_mask:0xf bank_mask:0xc bound_ctrl:1
	v_add_f32_dpp v12, v12, v12 quad_perm:[1,0,3,2] row_mask:0xf bank_mask:0xf bound_ctrl:1
	v_pk_mul_f32 v[6:7], v[128:129], v[116:117] op_sel_hi:[1,0]
	v_pk_mul_f32 v[8:9], v[130:131], v[116:117] op_sel_hi:[1,0]
	v_pk_fma_f32 v[6:7], v[2:3], v[120:121], v[6:7]
	v_pk_fma_f32 v[8:9], v[4:5], v[122:123], v[8:9]
	v_add_f32_dpp v12, v12, v12 quad_perm:[2,3,0,1] row_mask:0xf bank_mask:0xf bound_ctrl:1
	ds_read_b128 v[180:183], v84 offset:24960
	ds_read_b128 v[168:171], v84 offset:24192
	ds_read_b128 v[176:179], v84 offset:24704
	ds_read_b128 v[172:175], v84 offset:24448
	v_add_f32_dpp v12, v12, v12 row_half_mirror row_mask:0xf bank_mask:0xf bound_ctrl:1
	ds_read_b128 v[184:187], v84 offset:25216
	v_add_f32_dpp v100, v100, v100 row_half_mirror row_mask:0xf bank_mask:0x5 bound_ctrl:1
	v_add_f32_dpp v100, v104, v104 row_half_mirror row_mask:0xf bank_mask:0xa bound_ctrl:1
	v_add_f32_dpp v101, v101, v101 row_half_mirror row_mask:0xf bank_mask:0x5 bound_ctrl:1
	v_add_f32_dpp v12, v12, v12 row_mirror row_mask:0xf bank_mask:0xf bound_ctrl:1
	v_add_f32_dpp v101, v105, v105 row_half_mirror row_mask:0xf bank_mask:0xa bound_ctrl:1
	v_add_f32_dpp v102, v102, v102 row_half_mirror row_mask:0xf bank_mask:0x5 bound_ctrl:1
	v_add_f32_dpp v102, v106, v106 row_half_mirror row_mask:0xf bank_mask:0xa bound_ctrl:1
	v_add_f32_dpp v103, v103, v103 row_half_mirror row_mask:0xf bank_mask:0x5 bound_ctrl:1
	v_add_f32_dpp v103, v107, v107 row_half_mirror row_mask:0xf bank_mask:0xa bound_ctrl:1
	v_cndmask_b32_e64 v16, v102, v100, s[8:9]
	v_pk_fma_f32 v[2:3], v[124:125], v[12:13], v[6:7] op_sel_hi:[1,0,1] neg_lo:[0,1,0] neg_hi:[0,1,0]
	v_pk_fma_f32 v[4:5], v[126:127], v[12:13], v[8:9] op_sel_hi:[1,0,1] neg_lo:[0,1,0] neg_hi:[0,1,0]
	s_waitcnt lgkmcnt(5)
	v_pk_mul_f32 v[10:11], v[2:3], v[156:157]
	v_pk_fma_f32 v[10:11], v[4:5], v[158:159], v[10:11]
	v_pk_mul_f32 v[14:15], v[2:3], v[136:137]
	v_add_f32_e32 v12, v10, v11
	v_pk_fma_f32 v[14:15], v[4:5], v[138:139], v[14:15]
	v_add_f32_e64 v108, v14, v15
	v_pk_mul_f32 v[6:7], v[152:153], v[116:117] op_sel:[0,1] op_sel_hi:[1,1]
	v_pk_mul_f32 v[8:9], v[154:155], v[116:117] op_sel:[0,1] op_sel_hi:[1,1]
	v_add_f32_dpp v12, v12, v12 quad_perm:[1,0,3,2] row_mask:0xf bank_mask:0xf bound_ctrl:1
	v_pk_fma_f32 v[6:7], v[2:3], v[144:145], v[6:7]
	v_pk_fma_f32 v[8:9], v[4:5], v[146:147], v[8:9]
	ds_read_b128 v[34:37], v84 offset:26304
	ds_read_b128 v[22:25], v84 offset:25536
	v_add_f32_dpp v12, v12, v12 quad_perm:[2,3,0,1] row_mask:0xf bank_mask:0xf bound_ctrl:1
	ds_read_b128 v[30:33], v84 offset:26048
	ds_read_b128 v[26:29], v84 offset:25792
	ds_read_b128 v[38:41], v84 offset:26560
	v_cndmask_b32_e64 v17, v100, v102, s[8:9]
	v_add_f32_dpp v12, v12, v12 row_half_mirror row_mask:0xf bank_mask:0xf bound_ctrl:1
	s_nop 0
	v_add_f32_dpp v16, v17, v16 quad_perm:[2,3,0,1] row_mask:0xf bank_mask:0xf bound_ctrl:1
	v_cndmask_b32_e64 v18, v103, v101, s[8:9]
	v_cndmask_b32_e64 v19, v101, v103, s[8:9]
	s_nop 1
	v_add_f32_dpp v18, v19, v18 quad_perm:[2,3,0,1] row_mask:0xf bank_mask:0xf bound_ctrl:1
	v_add_f32_dpp v12, v12, v12 row_mirror row_mask:0xf bank_mask:0xf bound_ctrl:1
	v_cndmask_b32_e64 v17, v18, v16, s[10:11]
	v_cndmask_b32_e64 v19, v16, v18, s[10:11]
	s_nop 1
	v_add_f32_dpp v17, v19, v17 quad_perm:[1,0,3,2] row_mask:0xf bank_mask:0xf bound_ctrl:1
	global_store_dword v[88:89], v17, off
	v_pk_fma_f32 v[2:3], v[148:149], v[12:13], v[6:7] op_sel_hi:[1,0,1] neg_lo:[0,1,0] neg_hi:[0,1,0]
	v_pk_fma_f32 v[4:5], v[150:151], v[12:13], v[8:9] op_sel_hi:[1,0,1] neg_lo:[0,1,0] neg_hi:[0,1,0]
	s_waitcnt lgkmcnt(5)
	v_pk_mul_f32 v[10:11], v[2:3], v[180:181]
	v_pk_fma_f32 v[10:11], v[4:5], v[182:183], v[10:11]
	v_pk_mul_f32 v[14:15], v[2:3], v[160:161]
	v_add_f32_e32 v12, v10, v11
	v_pk_fma_f32 v[14:15], v[4:5], v[162:163], v[14:15]
	v_add_f32_e64 v109, v14, v15
	v_add_f32_dpp v12, v12, v12 quad_perm:[1,0,3,2] row_mask:0xf bank_mask:0xf bound_ctrl:1
	v_pk_mul_f32 v[6:7], v[176:177], v[118:119] op_sel_hi:[1,0]
	v_pk_mul_f32 v[8:9], v[178:179], v[118:119] op_sel_hi:[1,0]
	v_add_f32_dpp v12, v12, v12 quad_perm:[2,3,0,1] row_mask:0xf bank_mask:0xf bound_ctrl:1
	v_pk_fma_f32 v[6:7], v[2:3], v[168:169], v[6:7]
	v_pk_fma_f32 v[8:9], v[4:5], v[170:171], v[8:9]
	v_add_f32_dpp v12, v12, v12 row_half_mirror row_mask:0xf bank_mask:0xf bound_ctrl:1
	ds_read_b128 v[132:135], v84 offset:27648
	ds_read_b128 v[120:123], v84 offset:26880
	v_add_f32_dpp v12, v12, v12 row_mirror row_mask:0xf bank_mask:0xf bound_ctrl:1
	ds_read_b128 v[128:131], v84 offset:27392
	ds_read_b128 v[92:95], v96 offset:80
	ds_read_b128 v[124:127], v84 offset:27136
	ds_read_b128 v[136:139], v84 offset:27904
	v_pk_fma_f32 v[2:3], v[172:173], v[12:13], v[6:7] op_sel_hi:[1,0,1] neg_lo:[0,1,0] neg_hi:[0,1,0]
	v_pk_fma_f32 v[4:5], v[174:175], v[12:13], v[8:9] op_sel_hi:[1,0,1] neg_lo:[0,1,0] neg_hi:[0,1,0]
	s_waitcnt lgkmcnt(6)
; #define LAS __attribute__((address_space(3)))
; __device__ __forceinline__ float row16_sum(float v) { v += dpp_f<0xB1>(v); v += dpp_f<0x4E>(v); v += dpp_f<0x141>(v); v += dpp_f<0x140>(v); return v; }
; __device__ __forceinline__ void rwkv_scan_unit(LAS unsigned char* lds, const float* Wd, const float* V, const bf16_t* RKKB, float* Yraw, int p, int rg, int tid) {
;     ...
;             for (int st = 0; st < SCAN_CH; ++st) {
;                 f32x4 wn = w, bn = b, kn = k, kkn = kk, rn = r; float vn = v;
;                 if (st + 1 < SCAN_CH) { const int o = (st + 1) * SCAN_STEP_B;
;                     wn = *(LAS const f32x4*)(sl + o); bn = *(LAS const f32x4*)(sl + o + 256); kn = *(LAS const f32x4*)(sl + o + 512); kkn = *(LAS const f32x4*)(sl + o + 768); rn = *(LAS const f32x4*)(sl + o + 1024);
;                     vn = *(LAS const float*)(vl + o); }
;                 float sa = (S[0] * kk[0] + S[1] * kk[1]) + (S[2] * kk[2] + S[3] * kk[3]);
;                 const f32x4 kvt = k * v;
;                 sa = -row16_sum(sa);
;                 S = S * w + (b * sa + kvt);
;                 yp[st & 15] = (S[0] * r[0] + S[1] * r[1]) + (S[2] * r[2] + S[3] * r[3]);
;                 if ((st & 15) == 15) yo[(size_t)(st - 15) * 64] = tr16_sum(yp, kq);
;                 w = wn; b = bn; k = kn; kk = kkn; r = rn; v = vn;
;             }
	v_pk_mul_f32 v[10:11], v[2:3], v[34:35]
	v_pk_fma_f32 v[10:11], v[4:5], v[36:37], v[10:11]
	v_pk_mul_f32 v[14:15], v[2:3], v[184:185]
	v_add_f32_e32 v12, v10, v11
	v_pk_fma_f32 v[14:15], v[4:5], v[186:187], v[14:15]
	v_add_f32_e64 v110, v14, v15
	v_add_f32_dpp v12, v12, v12 quad_perm:[1,0,3,2] row_mask:0xf bank_mask:0xf bound_ctrl:1
	v_pk_mul_f32 v[6:7], v[30:31], v[118:119] op_sel:[0,1] op_sel_hi:[1,1]
	v_pk_mul_f32 v[8:9], v[32:33], v[118:119] op_sel:[0,1] op_sel_hi:[1,1]
	v_add_f32_dpp v12, v12, v12 quad_perm:[2,3,0,1] row_mask:0xf bank_mask:0xf bound_ctrl:1
	v_pk_fma_f32 v[6:7], v[2:3], v[22:23], v[6:7]
	v_pk_fma_f32 v[8:9], v[4:5], v[24:25], v[8:9]
	v_add_f32_dpp v12, v12, v12 row_half_mirror row_mask:0xf bank_mask:0xf bound_ctrl:1
	ds_read_b128 v[156:159], v84 offset:28992
	ds_read_b128 v[144:147], v84 offset:28224
	v_add_f32_dpp v12, v12, v12 row_mirror row_mask:0xf bank_mask:0xf bound_ctrl:1
	ds_read_b128 v[152:155], v84 offset:28736
	ds_read_b128 v[148:151], v84 offset:28480
	ds_read_b128 v[160:163], v84 offset:29248
	v_pk_fma_f32 v[2:3], v[26:27], v[12:13], v[6:7] op_sel_hi:[1,0,1] neg_lo:[0,1,0] neg_hi:[0,1,0]
	v_pk_fma_f32 v[4:5], v[28:29], v[12:13], v[8:9] op_sel_hi:[1,0,1] neg_lo:[0,1,0] neg_hi:[0,1,0]
	s_waitcnt lgkmcnt(5)
	v_pk_mul_f32 v[10:11], v[2:3], v[132:133]
	v_pk_fma_f32 v[10:11], v[4:5], v[134:135], v[10:11]
	v_pk_mul_f32 v[14:15], v[2:3], v[38:39]
	v_add_f32_e32 v12, v10, v11
	v_pk_fma_f32 v[14:15], v[4:5], v[40:41], v[14:15]
	v_add_f32_e64 v111, v14, v15
	v_add_f32_dpp v12, v12, v12 quad_perm:[1,0,3,2] row_mask:0xf bank_mask:0xf bound_ctrl:1
	v_pk_mul_f32 v[6:7], v[128:129], v[92:93] op_sel_hi:[1,0]
	v_pk_mul_f32 v[8:9], v[130:131], v[92:93] op_sel_hi:[1,0]
	v_add_f32_dpp v12, v12, v12 quad_perm:[2,3,0,1] row_mask:0xf bank_mask:0xf bound_ctrl:1
	v_pk_fma_f32 v[6:7], v[2:3], v[120:121], v[6:7]
	v_pk_fma_f32 v[8:9], v[4:5], v[122:123], v[8:9]
	v_add_f32_dpp v12, v12, v12 row_half_mirror row_mask:0xf bank_mask:0xf bound_ctrl:1
	ds_read_b128 v[180:183], v84 offset:30336
	ds_read_b128 v[168:171], v84 offset:29568
	v_add_f32_dpp v12, v12, v12 row_mirror row_mask:0xf bank_mask:0xf bound_ctrl:1
	ds_read_b128 v[176:179], v84 offset:30080
	ds_read_b128 v[172:175], v84 offset:29824
	ds_read_b128 v[184:187], v84 offset:30592
	v_pk_fma_f32 v[2:3], v[124:125], v[12:13], v[6:7] op_sel_hi:[1,0,1] neg_lo:[0,1,0] neg_hi:[0,1,0]
	v_pk_fma_f32 v[4:5], v[126:127], v[12:13], v[8:9] op_sel_hi:[1,0,1] neg_lo:[0,1,0] neg_hi:[0,1,0]
	s_waitcnt lgkmcnt(5)
	v_pk_mul_f32 v[10:11], v[2:3], v[156:157]
	v_pk_fma_f32 v[10:11], v[4:5], v[158:159], v[10:11]
	v_pk_mul_f32 v[14:15], v[2:3], v[136:137]
	v_add_f32_e32 v12, v10, v11
	v_pk_fma_f32 v[14:15], v[4:5], v[138:139], v[14:15]
	v_add_f32_e64 v112, v14, v15
	v_add_f32_dpp v12, v12, v12 quad_perm:[1,0,3,2] row_mask:0xf bank_mask:0xf bound_ctrl:1
	v_pk_mul_f32 v[6:7], v[152:153], v[92:93] op_sel:[0,1] op_sel_hi:[1,1]
	v_pk_mul_f32 v[8:9], v[154:155], v[92:93] op_sel:[0,1] op_sel_hi:[1,1]
	v_add_f32_dpp v12, v12, v12 quad_perm:[2,3,0,1] row_mask:0xf bank_mask:0xf bound_ctrl:1
	v_pk_fma_f32 v[6:7], v[2:3], v[144:145], v[6:7]
	v_pk_fma_f32 v[8:9], v[4:5], v[146:147], v[8:9]
	v_add_f32_dpp v12, v12, v12 row_half_mirror row_mask:0xf bank_mask:0xf bound_ctrl:1
	ds_read_b128 v[34:37], v84 offset:31680
	ds_read_b128 v[22:25], v84 offset:30912
	v_add_f32_dpp v12, v12, v12 row_mirror row_mask:0xf bank_mask:0xf bound_ctrl:1
	ds_read_b128 v[30:33], v84 offset:31424
	ds_read_b128 v[26:29], v84 offset:31168
	ds_read_b128 v[38:41], v84 offset:31936
	v_pk_fma_f32 v[2:3], v[148:149], v[12:13], v[6:7] op_sel_hi:[1,0,1] neg_lo:[0,1,0] neg_hi:[0,1,0]
	v_pk_fma_f32 v[4:5], v[150:151], v[12:13], v[8:9] op_sel_hi:[1,0,1] neg_lo:[0,1,0] neg_hi:[0,1,0]
	s_waitcnt lgkmcnt(5)
	v_pk_mul_f32 v[10:11], v[2:3], v[180:181]
	v_pk_fma_f32 v[10:11], v[4:5], v[182:183], v[10:11]
	v_pk_mul_f32 v[14:15], v[2:3], v[160:161]
	v_add_f32_e32 v12, v10, v11
	v_pk_fma_f32 v[14:15], v[4:5], v[162:163], v[14:15]
	v_add_f32_e64 v113, v14, v15
	v_add_f32_dpp v12, v12, v12 quad_perm:[1,0,3,2] row_mask:0xf bank_mask:0xf bound_ctrl:1
	v_pk_mul_f32 v[6:7], v[176:177], v[94:95] op_sel_hi:[1,0]
	v_pk_mul_f32 v[8:9], v[178:179], v[94:95] op_sel_hi:[1,0]
	v_add_f32_dpp v12, v12, v12 quad_perm:[2,3,0,1] row_mask:0xf bank_mask:0xf bound_ctrl:1
	v_pk_fma_f32 v[6:7], v[2:3], v[168:169], v[6:7]
	v_pk_fma_f32 v[8:9], v[4:5], v[170:171], v[8:9]
	v_add_f32_dpp v12, v12, v12 row_half_mirror row_mask:0xf bank_mask:0xf bound_ctrl:1
	ds_read_b128 v[132:135], v84 offset:33024
	ds_read_b128 v[120:123], v84 offset:32256
	v_add_f32_dpp v12, v12, v12 row_mirror row_mask:0xf bank_mask:0xf bound_ctrl:1
	ds_read_b128 v[128:131], v84 offset:32768
	ds_read_b128 v[116:119], v96 offset:96
	ds_read_b128 v[124:127], v84 offset:32512
	ds_read_b128 v[136:139], v84 offset:33280
	v_pk_fma_f32 v[2:3], v[172:173], v[12:13], v[6:7] op_sel_hi:[1,0,1] neg_lo:[0,1,0] neg_hi:[0,1,0]
	v_pk_fma_f32 v[4:5], v[174:175], v[12:13], v[8:9] op_sel_hi:[1,0,1] neg_lo:[0,1,0] neg_hi:[0,1,0]
	s_waitcnt lgkmcnt(6)
; #define LAS __attribute__((address_space(3)))
; template <int CTRL> __device__ __forceinline__ float dpp_f(float v) { return __int_as_float(__builtin_amdgcn_update_dpp(0, __float_as_int(v), CTRL, 0xf, 0xf, true)); }
; __device__ __forceinline__ float row16_sum(float v) { v += dpp_f<0xB1>(v); v += dpp_f<0x4E>(v); v += dpp_f<0x141>(v); v += dpp_f<0x140>(v); return v; }
; __device__ __forceinline__ float tr16_sum(const float (&p)[16], int kq) {
;     const bool b3 = (kq & 8) != 0, b2 = (kq & 4) != 0, b1 = (kq & 2) != 0, b0 = (kq & 1) != 0;
;     float q[8], r[4], u[2];
; #pragma unroll
;     for (int t = 0; t < 8; ++t) { const float keep = b3 ? p[t + 8] : p[t], send = b3 ? p[t] : p[t + 8]; q[t] = keep + dpp_f<0x140>(send); }
; #pragma unroll
;     for (int t = 0; t < 4; ++t) { const float keep = b2 ? q[t + 4] : q[t], send = b2 ? q[t] : q[t + 4]; r[t] = keep + dpp_f<0x141>(send); }
; #pragma unroll
;     for (int t = 0; t < 2; ++t) { const float keep = b1 ? r[t + 2] : r[t], send = b1 ? r[t] : r[t + 2]; u[t] = keep + dpp_f<0x4E>(send); }
;     const float keep = b0 ? u[1] : u[0], send = b0 ? u[0] : u[1];
;     return keep + dpp_f<0xB1>(send);
; __device__ __forceinline__ void rwkv_scan_unit(LAS unsigned char* lds, const float* Wd, const float* V, const bf16_t* RKKB, float* Yraw, int p, int rg, int tid) {
;     ...
;             for (int st = 0; st < SCAN_CH; ++st) {
;                 f32x4 wn = w, bn = b, kn = k, kkn = kk, rn = r; float vn = v;
;                 if (st + 1 < SCAN_CH) { const int o = (st + 1) * SCAN_STEP_B;
;                     wn = *(LAS const f32x4*)(sl + o); bn = *(LAS const f32x4*)(sl + o + 256); kn = *(LAS const f32x4*)(sl + o + 512); kkn = *(LAS const f32x4*)(sl + o + 768); rn = *(LAS const f32x4*)(sl + o + 1024);
;                     vn = *(LAS const float*)(vl + o); }
;                 float sa = (S[0] * kk[0] + S[1] * kk[1]) + (S[2] * kk[2] + S[3] * kk[3]);
;                 const f32x4 kvt = k * v;
;                 sa = -row16_sum(sa);
;                 S = S * w + (b * sa + kvt);
;                 yp[st & 15] = (S[0] * r[0] + S[1] * r[1]) + (S[2] * r[2] + S[3] * r[3]);
;                 if ((st & 15) == 15) yo[(size_t)(st - 15) * 64] = tr16_sum(yp, kq);
;                 w = wn; b = bn; k = kn; kk = kkn; r = rn; v = vn;
;             }
	v_pk_mul_f32 v[10:11], v[2:3], v[34:35]
	v_pk_fma_f32 v[10:11], v[4:5], v[36:37], v[10:11]
	v_pk_mul_f32 v[14:15], v[2:3], v[184:185]
	v_add_f32_e32 v12, v10, v11
	v_pk_fma_f32 v[14:15], v[4:5], v[186:187], v[14:15]
	v_add_f32_e64 v114, v14, v15
	v_add_f32_dpp v12, v12, v12 quad_perm:[1,0,3,2] row_mask:0xf bank_mask:0xf bound_ctrl:1
	v_pk_mul_f32 v[6:7], v[30:31], v[94:95] op_sel:[0,1] op_sel_hi:[1,1]
	v_pk_mul_f32 v[8:9], v[32:33], v[94:95] op_sel:[0,1] op_sel_hi:[1,1]
	v_add_f32_dpp v12, v12, v12 quad_perm:[2,3,0,1] row_mask:0xf bank_mask:0xf bound_ctrl:1
	v_pk_fma_f32 v[6:7], v[2:3], v[22:23], v[6:7]
	v_pk_fma_f32 v[8:9], v[4:5], v[24:25], v[8:9]
	v_add_f32_dpp v12, v12, v12 row_half_mirror row_mask:0xf bank_mask:0xf bound_ctrl:1
	ds_read_b128 v[156:159], v84 offset:34368
	ds_read_b128 v[144:147], v84 offset:33600
	v_add_f32_dpp v12, v12, v12 row_mirror row_mask:0xf bank_mask:0xf bound_ctrl:1
	ds_read_b128 v[152:155], v84 offset:34112
	ds_read_b128 v[148:151], v84 offset:33856
	ds_read_b128 v[160:163], v84 offset:34624
	v_pk_fma_f32 v[2:3], v[26:27], v[12:13], v[6:7] op_sel_hi:[1,0,1] neg_lo:[0,1,0] neg_hi:[0,1,0]
	v_pk_fma_f32 v[4:5], v[28:29], v[12:13], v[8:9] op_sel_hi:[1,0,1] neg_lo:[0,1,0] neg_hi:[0,1,0]
	s_waitcnt lgkmcnt(5)
	v_pk_mul_f32 v[10:11], v[2:3], v[132:133]
	v_pk_fma_f32 v[10:11], v[4:5], v[134:135], v[10:11]
	v_pk_mul_f32 v[14:15], v[2:3], v[38:39]
	v_add_f32_e32 v12, v10, v11
	v_pk_fma_f32 v[14:15], v[4:5], v[40:41], v[14:15]
	v_add_f32_e64 v115, v14, v15
	v_add_f32_dpp v12, v12, v12 quad_perm:[1,0,3,2] row_mask:0xf bank_mask:0xf bound_ctrl:1
	v_pk_mul_f32 v[6:7], v[128:129], v[116:117] op_sel_hi:[1,0]
	v_pk_mul_f32 v[8:9], v[130:131], v[116:117] op_sel_hi:[1,0]
	v_add_f32_dpp v12, v12, v12 quad_perm:[2,3,0,1] row_mask:0xf bank_mask:0xf bound_ctrl:1
	v_pk_fma_f32 v[6:7], v[2:3], v[120:121], v[6:7]
	v_pk_fma_f32 v[8:9], v[4:5], v[122:123], v[8:9]
	v_add_f32_dpp v12, v12, v12 row_half_mirror row_mask:0xf bank_mask:0xf bound_ctrl:1
	ds_read_b128 v[180:183], v84 offset:35712
	ds_read_b128 v[168:171], v84 offset:34944
	v_add_f32_dpp v12, v12, v12 row_mirror row_mask:0xf bank_mask:0xf bound_ctrl:1
	ds_read_b128 v[176:179], v84 offset:35456
	ds_read_b128 v[172:175], v84 offset:35200
	ds_read_b128 v[184:187], v84 offset:35968
	v_pk_fma_f32 v[2:3], v[124:125], v[12:13], v[6:7] op_sel_hi:[1,0,1] neg_lo:[0,1,0] neg_hi:[0,1,0]
	v_pk_fma_f32 v[4:5], v[126:127], v[12:13], v[8:9] op_sel_hi:[1,0,1] neg_lo:[0,1,0] neg_hi:[0,1,0]
	s_waitcnt lgkmcnt(5)
	v_pk_mul_f32 v[10:11], v[2:3], v[156:157]
	v_pk_fma_f32 v[10:11], v[4:5], v[158:159], v[10:11]
	v_pk_mul_f32 v[14:15], v[2:3], v[136:137]
	v_add_f32_e32 v12, v10, v11
	v_pk_fma_f32 v[14:15], v[4:5], v[138:139], v[14:15]
	v_add_f32_e64 v44, v14, v15
	v_add_f32_dpp v12, v12, v12 quad_perm:[1,0,3,2] row_mask:0xf bank_mask:0xf bound_ctrl:1
	v_add_f32_dpp v108, v108, v108 row_mirror row_mask:0xf bank_mask:0x3 bound_ctrl:1
	v_add_f32_dpp v108, v44, v44 row_mirror row_mask:0xf bank_mask:0xc bound_ctrl:1
	v_add_f32_dpp v12, v12, v12 quad_perm:[2,3,0,1] row_mask:0xf bank_mask:0xf bound_ctrl:1
	v_pk_mul_f32 v[6:7], v[152:153], v[116:117] op_sel:[0,1] op_sel_hi:[1,1]
	v_pk_mul_f32 v[8:9], v[154:155], v[116:117] op_sel:[0,1] op_sel_hi:[1,1]
	v_add_f32_dpp v12, v12, v12 row_half_mirror row_mask:0xf bank_mask:0xf bound_ctrl:1
	v_pk_fma_f32 v[6:7], v[2:3], v[144:145], v[6:7]
	v_pk_fma_f32 v[8:9], v[4:5], v[146:147], v[8:9]
	v_add_f32_dpp v12, v12, v12 row_mirror row_mask:0xf bank_mask:0xf bound_ctrl:1
	ds_read_b128 v[34:37], v84 offset:37056
	ds_read_b128 v[22:25], v84 offset:36288
	ds_read_b128 v[30:33], v84 offset:36800
	ds_read_b128 v[26:29], v84 offset:36544
	ds_read_b128 v[38:41], v84 offset:37312
	v_pk_fma_f32 v[2:3], v[148:149], v[12:13], v[6:7] op_sel_hi:[1,0,1] neg_lo:[0,1,0] neg_hi:[0,1,0]
	v_pk_fma_f32 v[4:5], v[150:151], v[12:13], v[8:9] op_sel_hi:[1,0,1] neg_lo:[0,1,0] neg_hi:[0,1,0]
	s_waitcnt lgkmcnt(5)
	v_pk_mul_f32 v[10:11], v[2:3], v[180:181]
	v_pk_fma_f32 v[10:11], v[4:5], v[182:183], v[10:11]
	v_pk_mul_f32 v[14:15], v[2:3], v[160:161]
	v_add_f32_e32 v12, v10, v11
	v_pk_fma_f32 v[14:15], v[4:5], v[162:163], v[14:15]
	v_add_f32_e64 v44, v14, v15
	v_add_f32_dpp v12, v12, v12 quad_perm:[1,0,3,2] row_mask:0xf bank_mask:0xf bound_ctrl:1
	v_add_f32_dpp v109, v109, v109 row_mirror row_mask:0xf bank_mask:0x3 bound_ctrl:1
	v_add_f32_dpp v109, v44, v44 row_mirror row_mask:0xf bank_mask:0xc bound_ctrl:1
	v_add_f32_dpp v12, v12, v12 quad_perm:[2,3,0,1] row_mask:0xf bank_mask:0xf bound_ctrl:1
	v_pk_mul_f32 v[6:7], v[176:177], v[118:119] op_sel_hi:[1,0]
	v_pk_mul_f32 v[8:9], v[178:179], v[118:119] op_sel_hi:[1,0]
	v_add_f32_dpp v12, v12, v12 row_half_mirror row_mask:0xf bank_mask:0xf bound_ctrl:1
	v_pk_fma_f32 v[6:7], v[2:3], v[168:169], v[6:7]
	v_pk_fma_f32 v[8:9], v[4:5], v[170:171], v[8:9]
	v_add_f32_dpp v12, v12, v12 row_mirror row_mask:0xf bank_mask:0xf bound_ctrl:1
	ds_read_b128 v[132:135], v84 offset:38400
	ds_read_b128 v[120:123], v84 offset:37632
	ds_read_b128 v[128:131], v84 offset:38144
	ds_read_b128 v[92:95], v96 offset:112
	ds_read_b128 v[124:127], v84 offset:37888
	ds_read_b128 v[136:139], v84 offset:38656
	v_pk_fma_f32 v[2:3], v[172:173], v[12:13], v[6:7] op_sel_hi:[1,0,1] neg_lo:[0,1,0] neg_hi:[0,1,0]
	v_pk_fma_f32 v[4:5], v[174:175], v[12:13], v[8:9] op_sel_hi:[1,0,1] neg_lo:[0,1,0] neg_hi:[0,1,0]
	s_waitcnt lgkmcnt(6)
; #define LAS __attribute__((address_space(3)))
; template <int CTRL> __device__ __forceinline__ float dpp_f(float v) { return __int_as_float(__builtin_amdgcn_update_dpp(0, __float_as_int(v), CTRL, 0xf, 0xf, true)); }
; __device__ __forceinline__ float row16_sum(float v) { v += dpp_f<0xB1>(v); v += dpp_f<0x4E>(v); v += dpp_f<0x141>(v); v += dpp_f<0x140>(v); return v; }
; __device__ __forceinline__ float tr16_sum(const float (&p)[16], int kq) {
;     const bool b3 = (kq & 8) != 0, b2 = (kq & 4) != 0, b1 = (kq & 2) != 0, b0 = (kq & 1) != 0;
;     float q[8], r[4], u[2];
; #pragma unroll
;     for (int t = 0; t < 8; ++t) { const float keep = b3 ? p[t + 8] : p[t], send = b3 ? p[t] : p[t + 8]; q[t] = keep + dpp_f<0x140>(send); }
; #pragma unroll
;     for (int t = 0; t < 4; ++t) { const float keep = b2 ? q[t + 4] : q[t], send = b2 ? q[t] : q[t + 4]; r[t] = keep + dpp_f<0x141>(send); }
; #pragma unroll
;     for (int t = 0; t < 2; ++t) { const float keep = b1 ? r[t + 2] : r[t], send = b1 ? r[t] : r[t + 2]; u[t] = keep + dpp_f<0x4E>(send); }
;     const float keep = b0 ? u[1] : u[0], send = b0 ? u[0] : u[1];
;     return keep + dpp_f<0xB1>(send);
; __device__ __forceinline__ void rwkv_scan_unit(LAS unsigned char* lds, const float* Wd, const float* V, const bf16_t* RKKB, float* Yraw, int p, int rg, int tid) {
;     ...
;             for (int st = 0; st < SCAN_CH; ++st) {
;                 f32x4 wn = w, bn = b, kn = k, kkn = kk, rn = r; float vn = v;
;                 if (st + 1 < SCAN_CH) { const int o = (st + 1) * SCAN_STEP_B;
;                     wn = *(LAS const f32x4*)(sl + o); bn = *(LAS const f32x4*)(sl + o + 256); kn = *(LAS const f32x4*)(sl + o + 512); kkn = *(LAS const f32x4*)(sl + o + 768); rn = *(LAS const f32x4*)(sl + o + 1024);
;                     vn = *(LAS const float*)(vl + o); }
;                 float sa = (S[0] * kk[0] + S[1] * kk[1]) + (S[2] * kk[2] + S[3] * kk[3]);
;                 const f32x4 kvt = k * v;
;                 sa = -row16_sum(sa);
;                 S = S * w + (b * sa + kvt);
;                 yp[st & 15] = (S[0] * r[0] + S[1] * r[1]) + (S[2] * r[2] + S[3] * r[3]);
;                 if ((st & 15) == 15) yo[(size_t)(st - 15) * 64] = tr16_sum(yp, kq);
;                 w = wn; b = bn; k = kn; kk = kkn; r = rn; v = vn;
;             }
	v_pk_mul_f32 v[10:11], v[2:3], v[34:35]
	v_pk_fma_f32 v[10:11], v[4:5], v[36:37], v[10:11]
	v_pk_mul_f32 v[14:15], v[2:3], v[184:185]
	v_add_f32_e32 v12, v10, v11
	v_pk_fma_f32 v[14:15], v[4:5], v[186:187], v[14:15]
	v_add_f32_e64 v44, v14, v15
	v_add_f32_dpp v12, v12, v12 quad_perm:[1,0,3,2] row_mask:0xf bank_mask:0xf bound_ctrl:1
	v_add_f32_dpp v110, v110, v110 row_mirror row_mask:0xf bank_mask:0x3 bound_ctrl:1
	v_add_f32_dpp v110, v44, v44 row_mirror row_mask:0xf bank_mask:0xc bound_ctrl:1
	v_add_f32_dpp v12, v12, v12 quad_perm:[2,3,0,1] row_mask:0xf bank_mask:0xf bound_ctrl:1
	v_pk_mul_f32 v[6:7], v[30:31], v[118:119] op_sel:[0,1] op_sel_hi:[1,1]
	v_pk_mul_f32 v[8:9], v[32:33], v[118:119] op_sel:[0,1] op_sel_hi:[1,1]
	v_add_f32_dpp v12, v12, v12 row_half_mirror row_mask:0xf bank_mask:0xf bound_ctrl:1
	v_pk_fma_f32 v[6:7], v[2:3], v[22:23], v[6:7]
	v_pk_fma_f32 v[8:9], v[4:5], v[24:25], v[8:9]
	v_add_f32_dpp v12, v12, v12 row_mirror row_mask:0xf bank_mask:0xf bound_ctrl:1
	ds_read_b128 v[156:159], v84 offset:39744
	ds_read_b128 v[144:147], v84 offset:38976
	ds_read_b128 v[152:155], v84 offset:39488
	ds_read_b128 v[148:151], v84 offset:39232
	ds_read_b128 v[160:163], v84 offset:40000
	v_pk_fma_f32 v[2:3], v[26:27], v[12:13], v[6:7] op_sel_hi:[1,0,1] neg_lo:[0,1,0] neg_hi:[0,1,0]
	v_pk_fma_f32 v[4:5], v[28:29], v[12:13], v[8:9] op_sel_hi:[1,0,1] neg_lo:[0,1,0] neg_hi:[0,1,0]
	s_waitcnt lgkmcnt(5)
	v_pk_mul_f32 v[10:11], v[2:3], v[132:133]
	v_pk_fma_f32 v[10:11], v[4:5], v[134:135], v[10:11]
	v_pk_mul_f32 v[14:15], v[2:3], v[38:39]
	v_add_f32_e32 v12, v10, v11
	v_pk_fma_f32 v[14:15], v[4:5], v[40:41], v[14:15]
	v_add_f32_e64 v44, v14, v15
	v_add_f32_dpp v12, v12, v12 quad_perm:[1,0,3,2] row_mask:0xf bank_mask:0xf bound_ctrl:1
	v_add_f32_dpp v111, v111, v111 row_mirror row_mask:0xf bank_mask:0x3 bound_ctrl:1
	v_add_f32_dpp v111, v44, v44 row_mirror row_mask:0xf bank_mask:0xc bound_ctrl:1
	v_add_f32_dpp v12, v12, v12 quad_perm:[2,3,0,1] row_mask:0xf bank_mask:0xf bound_ctrl:1
	v_pk_mul_f32 v[6:7], v[128:129], v[92:93] op_sel_hi:[1,0]
	v_pk_mul_f32 v[8:9], v[130:131], v[92:93] op_sel_hi:[1,0]
	v_add_f32_dpp v12, v12, v12 row_half_mirror row_mask:0xf bank_mask:0xf bound_ctrl:1
	v_pk_fma_f32 v[6:7], v[2:3], v[120:121], v[6:7]
	v_pk_fma_f32 v[8:9], v[4:5], v[122:123], v[8:9]
	v_add_f32_dpp v12, v12, v12 row_mirror row_mask:0xf bank_mask:0xf bound_ctrl:1
	ds_read_b128 v[180:183], v84 offset:41088
	ds_read_b128 v[168:171], v84 offset:40320
	ds_read_b128 v[176:179], v84 offset:40832
	ds_read_b128 v[172:175], v84 offset:40576
	ds_read_b128 v[184:187], v84 offset:41344
	v_pk_fma_f32 v[2:3], v[124:125], v[12:13], v[6:7] op_sel_hi:[1,0,1] neg_lo:[0,1,0] neg_hi:[0,1,0]
	v_pk_fma_f32 v[4:5], v[126:127], v[12:13], v[8:9] op_sel_hi:[1,0,1] neg_lo:[0,1,0] neg_hi:[0,1,0]
	s_waitcnt lgkmcnt(5)
	v_pk_mul_f32 v[10:11], v[2:3], v[156:157]
	v_pk_fma_f32 v[10:11], v[4:5], v[158:159], v[10:11]
	v_pk_mul_f32 v[14:15], v[2:3], v[136:137]
	v_add_f32_e32 v12, v10, v11
	v_pk_fma_f32 v[14:15], v[4:5], v[138:139], v[14:15]
	v_add_f32_e64 v44, v14, v15
	v_add_f32_dpp v12, v12, v12 quad_perm:[1,0,3,2] row_mask:0xf bank_mask:0xf bound_ctrl:1
	v_add_f32_dpp v112, v112, v112 row_mirror row_mask:0xf bank_mask:0x3 bound_ctrl:1
	v_add_f32_dpp v112, v44, v44 row_mirror row_mask:0xf bank_mask:0xc bound_ctrl:1
	v_add_f32_dpp v12, v12, v12 quad_perm:[2,3,0,1] row_mask:0xf bank_mask:0xf bound_ctrl:1
	v_pk_mul_f32 v[6:7], v[152:153], v[92:93] op_sel:[0,1] op_sel_hi:[1,1]
	v_pk_mul_f32 v[8:9], v[154:155], v[92:93] op_sel:[0,1] op_sel_hi:[1,1]
	v_add_f32_dpp v12, v12, v12 row_half_mirror row_mask:0xf bank_mask:0xf bound_ctrl:1
	v_pk_fma_f32 v[6:7], v[2:3], v[144:145], v[6:7]
	v_pk_fma_f32 v[8:9], v[4:5], v[146:147], v[8:9]
	v_add_f32_dpp v12, v12, v12 row_mirror row_mask:0xf bank_mask:0xf bound_ctrl:1
	ds_read_b128 v[34:37], v84 offset:42432
	ds_read_b128 v[22:25], v84 offset:41664
	ds_read_b128 v[30:33], v84 offset:42176
	ds_read_b128 v[26:29], v84 offset:41920
	ds_read_b128 v[38:41], v84 offset:42688
	v_pk_fma_f32 v[2:3], v[148:149], v[12:13], v[6:7] op_sel_hi:[1,0,1] neg_lo:[0,1,0] neg_hi:[0,1,0]
	v_pk_fma_f32 v[4:5], v[150:151], v[12:13], v[8:9] op_sel_hi:[1,0,1] neg_lo:[0,1,0] neg_hi:[0,1,0]
	s_waitcnt lgkmcnt(5)
; #define LAS __attribute__((address_space(3)))
; template <int CTRL> __device__ __forceinline__ float dpp_f(float v) { return __int_as_float(__builtin_amdgcn_update_dpp(0, __float_as_int(v), CTRL, 0xf, 0xf, true)); }
; __device__ __forceinline__ float row16_sum(float v) { v += dpp_f<0xB1>(v); v += dpp_f<0x4E>(v); v += dpp_f<0x141>(v); v += dpp_f<0x140>(v); return v; }
; __device__ __forceinline__ float tr16_sum(const float (&p)[16], int kq) {
;     const bool b3 = (kq & 8) != 0, b2 = (kq & 4) != 0, b1 = (kq & 2) != 0, b0 = (kq & 1) != 0;
;     float q[8], r[4], u[2];
; #pragma unroll
;     for (int t = 0; t < 8; ++t) { const float keep = b3 ? p[t + 8] : p[t], send = b3 ? p[t] : p[t + 8]; q[t] = keep + dpp_f<0x140>(send); }
; #pragma unroll
;     for (int t = 0; t < 4; ++t) { const float keep = b2 ? q[t + 4] : q[t], send = b2 ? q[t] : q[t + 4]; r[t] = keep + dpp_f<0x141>(send); }
; #pragma unroll
;     for (int t = 0; t < 2; ++t) { const float keep = b1 ? r[t + 2] : r[t], send = b1 ? r[t] : r[t + 2]; u[t] = keep + dpp_f<0x4E>(send); }
;     const float keep = b0 ? u[1] : u[0], send = b0 ? u[0] : u[1];
;     return keep + dpp_f<0xB1>(send);
; __device__ __forceinline__ void rwkv_scan_unit(LAS unsigned char* lds, const float* Wd, const float* V, const bf16_t* RKKB, float* Yraw, int p, int rg, int tid) {
;     ...
;             for (int st = 0; st < SCAN_CH; ++st) {
;                 f32x4 wn = w, bn = b, kn = k, kkn = kk, rn = r; float vn = v;
;                 if (st + 1 < SCAN_CH) { const int o = (st + 1) * SCAN_STEP_B;
;                     wn = *(LAS const f32x4*)(sl + o); bn = *(LAS const f32x4*)(sl + o + 256); kn = *(LAS const f32x4*)(sl + o + 512); kkn = *(LAS const f32x4*)(sl + o + 768); rn = *(LAS const f32x4*)(sl + o + 1024);
;                     vn = *(LAS const float*)(vl + o); }
;                 float sa = (S[0] * kk[0] + S[1] * kk[1]) + (S[2] * kk[2] + S[3] * kk[3]);
;                 const f32x4 kvt = k * v;
;                 sa = -row16_sum(sa);
;                 S = S * w + (b * sa + kvt);
;                 yp[st & 15] = (S[0] * r[0] + S[1] * r[1]) + (S[2] * r[2] + S[3] * r[3]);
;                 if ((st & 15) == 15) yo[(size_t)(st - 15) * 64] = tr16_sum(yp, kq);
;                 w = wn; b = bn; k = kn; kk = kkn; r = rn; v = vn;
;             }
;         }
;         __syncthreads();
;     }
	v_pk_mul_f32 v[10:11], v[2:3], v[180:181]
	v_pk_fma_f32 v[10:11], v[4:5], v[182:183], v[10:11]
	v_pk_mul_f32 v[14:15], v[2:3], v[160:161]
	v_add_f32_e32 v12, v10, v11
	v_pk_fma_f32 v[14:15], v[4:5], v[162:163], v[14:15]
	v_add_f32_e64 v44, v14, v15
	v_add_f32_dpp v12, v12, v12 quad_perm:[1,0,3,2] row_mask:0xf bank_mask:0xf bound_ctrl:1
	v_add_f32_dpp v113, v113, v113 row_mirror row_mask:0xf bank_mask:0x3 bound_ctrl:1
	v_add_f32_dpp v113, v44, v44 row_mirror row_mask:0xf bank_mask:0xc bound_ctrl:1
	v_add_f32_dpp v12, v12, v12 quad_perm:[2,3,0,1] row_mask:0xf bank_mask:0xf bound_ctrl:1
	v_pk_mul_f32 v[6:7], v[176:177], v[94:95] op_sel_hi:[1,0]
	v_pk_mul_f32 v[8:9], v[178:179], v[94:95] op_sel_hi:[1,0]
	v_add_f32_dpp v12, v12, v12 row_half_mirror row_mask:0xf bank_mask:0xf bound_ctrl:1
	v_pk_fma_f32 v[6:7], v[2:3], v[168:169], v[6:7]
	v_pk_fma_f32 v[8:9], v[4:5], v[170:171], v[8:9]
	v_add_f32_dpp v12, v12, v12 row_mirror row_mask:0xf bank_mask:0xf bound_ctrl:1
	ds_read_b128 v[132:135], v86 offset:768
	ds_read_b128 v[120:123], v86
	ds_read_b128 v[128:131], v86 offset:512
	ds_read_b128 v[116:119], v97
	ds_read_b128 v[124:127], v86 offset:256
	ds_read_b128 v[136:139], v86 offset:1024
	v_pk_fma_f32 v[2:3], v[172:173], v[12:13], v[6:7] op_sel_hi:[1,0,1] neg_lo:[0,1,0] neg_hi:[0,1,0]
	v_pk_fma_f32 v[4:5], v[174:175], v[12:13], v[8:9] op_sel_hi:[1,0,1] neg_lo:[0,1,0] neg_hi:[0,1,0]
	s_waitcnt lgkmcnt(6)
	v_pk_mul_f32 v[10:11], v[2:3], v[34:35]
	v_pk_fma_f32 v[10:11], v[4:5], v[36:37], v[10:11]
	v_pk_mul_f32 v[14:15], v[2:3], v[184:185]
	v_add_f32_e32 v12, v10, v11
	v_pk_fma_f32 v[14:15], v[4:5], v[186:187], v[14:15]
	v_add_f32_e64 v44, v14, v15
	v_add_f32_dpp v12, v12, v12 quad_perm:[1,0,3,2] row_mask:0xf bank_mask:0xf bound_ctrl:1
	v_add_f32_dpp v114, v114, v114 row_mirror row_mask:0xf bank_mask:0x3 bound_ctrl:1
	v_add_f32_dpp v114, v44, v44 row_mirror row_mask:0xf bank_mask:0xc bound_ctrl:1
	v_add_f32_dpp v12, v12, v12 quad_perm:[2,3,0,1] row_mask:0xf bank_mask:0xf bound_ctrl:1
	v_pk_mul_f32 v[6:7], v[30:31], v[94:95] op_sel:[0,1] op_sel_hi:[1,1]
	v_pk_mul_f32 v[8:9], v[32:33], v[94:95] op_sel:[0,1] op_sel_hi:[1,1]
	v_add_f32_dpp v12, v12, v12 row_half_mirror row_mask:0xf bank_mask:0xf bound_ctrl:1
	v_pk_fma_f32 v[6:7], v[2:3], v[22:23], v[6:7]
	v_pk_fma_f32 v[8:9], v[4:5], v[24:25], v[8:9]
	v_add_f32_dpp v12, v12, v12 row_mirror row_mask:0xf bank_mask:0xf bound_ctrl:1
	ds_read_b128 v[156:159], v86 offset:2112
	ds_read_b128 v[144:147], v86 offset:1344
	ds_read_b128 v[152:155], v86 offset:1856
	ds_read_b128 v[148:151], v86 offset:1600
	ds_read_b128 v[160:163], v86 offset:2368
	v_pk_fma_f32 v[2:3], v[26:27], v[12:13], v[6:7] op_sel_hi:[1,0,1] neg_lo:[0,1,0] neg_hi:[0,1,0]
	v_pk_fma_f32 v[4:5], v[28:29], v[12:13], v[8:9] op_sel_hi:[1,0,1] neg_lo:[0,1,0] neg_hi:[0,1,0]
	v_pk_mul_f32 v[14:15], v[2:3], v[38:39]
	v_pk_fma_f32 v[14:15], v[4:5], v[40:41], v[14:15]
	v_add_f32_e64 v44, v14, v15
	v_add_f32_dpp v115, v115, v115 row_mirror row_mask:0xf bank_mask:0x3 bound_ctrl:1
	s_nop 0
	v_add_f32_dpp v115, v44, v44 row_mirror row_mask:0xf bank_mask:0xc bound_ctrl:1
	v_add_f32_dpp v108, v108, v108 row_half_mirror row_mask:0xf bank_mask:0x5 bound_ctrl:1
	v_add_f32_dpp v108, v112, v112 row_half_mirror row_mask:0xf bank_mask:0xa bound_ctrl:1
	v_add_f32_dpp v109, v109, v109 row_half_mirror row_mask:0xf bank_mask:0x5 bound_ctrl:1
	v_add_f32_dpp v109, v113, v113 row_half_mirror row_mask:0xf bank_mask:0xa bound_ctrl:1
	v_add_f32_dpp v110, v110, v110 row_half_mirror row_mask:0xf bank_mask:0x5 bound_ctrl:1
	v_add_f32_dpp v110, v114, v114 row_half_mirror row_mask:0xf bank_mask:0xa bound_ctrl:1
	v_add_f32_dpp v111, v111, v111 row_half_mirror row_mask:0xf bank_mask:0x5 bound_ctrl:1
	v_add_f32_dpp v111, v115, v115 row_half_mirror row_mask:0xf bank_mask:0xa bound_ctrl:1
	v_cndmask_b32_e64 v16, v110, v108, s[8:9]
	v_cndmask_b32_e64 v17, v108, v110, s[8:9]
	s_nop 1
	v_add_f32_dpp v16, v17, v16 quad_perm:[2,3,0,1] row_mask:0xf bank_mask:0xf bound_ctrl:1
	v_cndmask_b32_e64 v18, v111, v109, s[8:9]
	v_cndmask_b32_e64 v19, v109, v111, s[8:9]
	s_nop 1
	v_add_f32_dpp v18, v19, v18 quad_perm:[2,3,0,1] row_mask:0xf bank_mask:0xf bound_ctrl:1
	v_cndmask_b32_e64 v17, v18, v16, s[10:11]
	v_cndmask_b32_e64 v19, v16, v18, s[10:11]
	s_nop 1
	v_add_f32_dpp v17, v19, v17 quad_perm:[1,0,3,2] row_mask:0xf bank_mask:0xf bound_ctrl:1
	global_store_dword v[90:91], v17, off
	s_add_i32 s22, s22, 1
	s_mov_b64 s[18:19], 0x2000
	v_lshl_add_u64 v[60:61], v[60:61], 0, s[18:19]
	s_mov_b64 s[68:69], 0x2000
	s_cmpk_eq_i32 s22, 0x80
	s_barrier
	s_cbranch_scc1 .LBB0_370
	s_branch .Lscan_top
	s_nop 0
	s_nop 0
	s_nop 0
	s_nop 0
	s_nop 0
	s_nop 0
	s_nop 0
	s_nop 0
	s_nop 0
	s_nop 0
	s_nop 0
	s_nop 0
	s_nop 0
	s_nop 0
	s_nop 0
